# P3 v4: LDS-DMA ring + wave specialisation (waves 0-3 output tiles sharing q operand, waves 4-7 own state S), 104 instead of 144 ds_read_b128 per step
# speedup vs baseline: 1.0065x; 1.0065x over previous
; #define LAS __attribute__((address_space(3)))
; __device__ __forceinline__ void gla_scan_item(const Ctx& C, int item, LAS unsigned char* lds, int tid) {
;     const int jx = item >> 3, bh = (item & 7) * 4 + (jx >> 3), sl = jx & 7, b = bh >> 2, h = bh & 3;
;     LAS bf16* Aq = (LAS bf16*)lds;
;     LAS bf16* Bc = (LAS bf16*)(lds + 25600);
;     LAS bf16* Kt = (LAS bf16*)(lds + 38400);
;     const int wave = tid >> 6, lane = tid & 63, l15 = lane & 15, quad = lane >> 4;
;     f32x4 S[2] = {(f32x4){0.f, 0.f, 0.f, 0.f}, (f32x4){0.f, 0.f, 0.f, 0.f}};
;     *(LAS u32x4*)(Bc + (tid >> 4) * 200 + (tid & 15) * 8) = (u32x4){0u, 0u, 0u, 0u};
;     u32x4 rq0A, rq1A, rsA, rk0A, rk1A, rvA = (u32x4){0u, 0u, 0u, 0u}; f32x4 rdA;
;     u32x4 rq0B, rq1B, rsB, rk0B, rk1B, rvB = (u32x4){0u, 0u, 0u, 0u}; f32x4 rdB;
.LBB0_428:
	s_cmp_lt_i32 s96, 4
	s_cselect_b64 s[4:5], -1, 0
	s_add_u32 s6, s94, 0xb300000
	s_addc_u32 s7, s95, 0
	s_and_b64 s[0:1], s[4:5], s[0:1]
	s_andn2_b64 vcc, exec, s[0:1]
	s_cbranch_vccnz .LBB0_496
	s_cmpk_gt_i32 s2, 0xff
	s_cbranch_scc1 .LBB0_496
	v_readfirstlane_b32 s32, v163
	v_and_b32_e32 v208, 63, v162
	v_and_b32_e32 v207, 15, v162
	v_bfe_u32 v206, v162, 4, 2
	v_lshrrev_b32_e32 v205, 4, v208
	v_lshl_add_u32 v205, v163, 3, v205
	v_and_b32_e32 v204, 15, v205
	v_xor_b32_e32 v204, v204, v207
	v_lshlrev_b32_e32 v255, 10, v205
	v_lshl_add_u32 v255, v204, 4, v255
	v_lshrrev_b32_e32 v205, 4, v208
	v_lshl_add_u32 v205, v163, 3, v205
	v_add_u32_e32 v205, 4, v205
	v_and_b32_e32 v204, 15, v205
	v_xor_b32_e32 v204, v204, v207
	v_lshlrev_b32_e32 v254, 10, v205
	v_lshl_add_u32 v254, v204, 4, v254
	v_lshrrev_b32_e32 v205, 3, v208
	v_lshl_add_u32 v205, v163, 3, v205
	v_bfe_u32 v204, v205, 1, 3
	v_and_b32_e32 v203, 7, v208
	v_xor_b32_e32 v204, v204, v203
	v_lshlrev_b32_e32 v253, 7, v205
	v_lshl_add_u32 v253, v204, 4, v253
	v_lshrrev_b32_e32 v205, 3, v208
	v_lshl_add_u32 v205, v163, 4, v205
	v_bfe_u32 v204, v205, 1, 3
	v_and_b32_e32 v203, 7, v208
	v_xor_b32_e32 v204, v204, v203
	v_lshlrev_b32_e32 v252, 7, v205
	v_lshl_add_u32 v252, v204, 4, v252
	v_lshrrev_b32_e32 v205, 3, v208
	v_lshl_add_u32 v205, v163, 4, v205
	v_add_u32_e32 v205, 8, v205
	v_bfe_u32 v204, v205, 1, 3
	v_and_b32_e32 v203, 7, v208
	v_xor_b32_e32 v204, v204, v203
	v_lshlrev_b32_e32 v251, 7, v205
	v_lshl_add_u32 v251, v204, 4, v251
	s_lshl_b32 s46, s32, 11
	s_lshl_b32 s47, s32, 10
	s_add_i32 s47, s47, 0x4000
	s_add_i32 s48, s46, 0x6000
	v_and_b32_e32 v205, 3, v163
	v_lshl_add_u32 v205, v205, 4, v207
	v_or_b32_e32 v204, 0, v206
	v_and_b32_e32 v203, 15, v205
	v_xor_b32_e32 v204, v204, v203
	v_lshlrev_b32_e32 v244, 8, v205
	v_lshl_add_u32 v244, v204, 4, v244
	v_or_b32_e32 v204, 4, v206
	v_and_b32_e32 v203, 15, v205
	v_xor_b32_e32 v204, v204, v203
	v_lshlrev_b32_e32 v243, 8, v205
	v_lshl_add_u32 v243, v204, 4, v243
	v_or_b32_e32 v204, 8, v206
	v_and_b32_e32 v203, 15, v205
	v_xor_b32_e32 v204, v204, v203
	v_lshlrev_b32_e32 v242, 8, v205
	v_lshl_add_u32 v242, v204, 4, v242
	v_or_b32_e32 v204, 12, v206
	v_and_b32_e32 v203, 15, v205
	v_xor_b32_e32 v204, v204, v203
	v_lshlrev_b32_e32 v241, 8, v205
	v_lshl_add_u32 v241, v204, 4, v241
	v_or_b32_e32 v204, 0, v206
	v_bfe_u32 v203, v205, 1, 3
	v_xor_b32_e32 v204, v204, v203
	v_lshlrev_b32_e32 v234, 7, v205
	v_lshl_add_u32 v234, v204, 4, v234
	v_add_u32_e32 v234, 0x4000, v234
	v_or_b32_e32 v204, 4, v206
	v_bfe_u32 v203, v205, 1, 3
	v_xor_b32_e32 v204, v204, v203
	v_lshlrev_b32_e32 v233, 7, v205
	v_lshl_add_u32 v233, v204, 4, v233
	v_add_u32_e32 v233, 0x4000, v233
	v_lshlrev_b32_e32 v248, 11, v205
	v_lshl_add_u32 v248, v206, 3, v248
	v_or_b32_e32 v204, 0, v206
	v_and_b32_e32 v203, 15, v207
	v_xor_b32_e32 v204, v204, v203
	v_lshlrev_b32_e32 v226, 8, v207
	v_lshl_add_u32 v226, v204, 4, v226
	v_add_u32_e32 v226, 0x1e000, v226
	v_or_b32_e32 v204, 4, v206
	v_and_b32_e32 v203, 15, v207
	v_xor_b32_e32 v204, v204, v203
	v_lshlrev_b32_e32 v225, 8, v207
	v_lshl_add_u32 v225, v204, 4, v225
	v_add_u32_e32 v225, 0x1e000, v225
	v_or_b32_e32 v204, 8, v206
	v_and_b32_e32 v203, 15, v207
	v_xor_b32_e32 v204, v204, v203
	v_lshlrev_b32_e32 v224, 8, v207
	v_lshl_add_u32 v224, v204, 4, v224
	v_add_u32_e32 v224, 0x1e000, v224
	v_or_b32_e32 v204, 12, v206
	v_and_b32_e32 v203, 15, v207
	v_xor_b32_e32 v204, v204, v203
	v_lshlrev_b32_e32 v223, 8, v207
	v_lshl_add_u32 v223, v204, 4, v223
	v_add_u32_e32 v223, 0x1e000, v223
	v_or_b32_e32 v204, 0, v206
	v_bfe_u32 v203, v207, 1, 3
	v_xor_b32_e32 v204, v204, v203
	v_lshlrev_b32_e32 v222, 7, v207
	v_lshl_add_u32 v222, v204, 4, v222
	v_add_u32_e32 v222, 0x20100, v222
	v_or_b32_e32 v204, 4, v206
	v_bfe_u32 v203, v207, 1, 3
	v_xor_b32_e32 v204, v204, v203
	v_lshlrev_b32_e32 v221, 7, v207
	v_lshl_add_u32 v221, v204, 4, v221
	v_add_u32_e32 v221, 0x20100, v221
	v_and_b32_e32 v205, 3, v163
	v_lshl_add_u32 v205, v205, 5, v207
	v_or_b32_e32 v204, 0, v206
	v_bfe_u32 v203, v205, 1, 3
	v_xor_b32_e32 v204, v204, v203
	v_lshlrev_b32_e32 v230, 7, v205
	v_lshl_add_u32 v230, v204, 4, v230
	v_add_u32_e32 v230, 0x6000, v230
	v_or_b32_e32 v204, 4, v206
	v_bfe_u32 v203, v205, 1, 3
	v_xor_b32_e32 v204, v204, v203
	v_lshlrev_b32_e32 v229, 7, v205
	v_lshl_add_u32 v229, v204, 4, v229
	v_add_u32_e32 v229, 0x6000, v229
	v_or_b32_e32 v204, 0, v206
	v_bfe_u32 v203, v207, 1, 3
	v_xor_b32_e32 v204, v204, v203
	v_lshlrev_b32_e32 v220, 7, v207
	v_lshl_add_u32 v220, v204, 4, v220
	v_add_u32_e32 v220, 0x20100, v220
	v_or_b32_e32 v204, 4, v206
	v_bfe_u32 v203, v207, 1, 3
	v_xor_b32_e32 v204, v204, v203
	v_lshlrev_b32_e32 v219, 7, v207
	v_lshl_add_u32 v219, v204, 4, v219
	v_add_u32_e32 v219, 0x20100, v219
	v_add_u32_e32 v240, 0x14000, v244
	v_add_u32_e32 v239, 0x14000, v243
	v_add_u32_e32 v238, 0x14000, v242
	v_add_u32_e32 v235, 0x14000, v241
	v_add_u32_e32 v232, 0x14000, v234
	v_add_u32_e32 v231, 0x14000, v233
	v_add_u32_e32 v228, 0x14000, v230
	v_add_u32_e32 v227, 0x14000, v229
	v_and_b32_e32 v205, 3, v163
	v_lshrrev_b32_e32 v204, 1, v206
	v_lshl_add_u32 v204, v205, 2, v204
	v_xor_b32_e32 v204, v204, v207
	v_lshlrev_b32_e32 v218, 8, v207
	v_lshl_add_u32 v218, v204, 4, v218
	v_and_b32_e32 v204, 1, v206
	v_lshl_add_u32 v218, v204, 3, v218
	v_add_u32_e32 v218, 0x1e000, v218
	v_and_b32_e32 v205, 3, v163
	v_lshrrev_b32_e32 v204, 1, v206
	v_lshl_add_u32 v204, v205, 2, v204
	v_add_u32_e32 v204, 2, v204
	v_xor_b32_e32 v204, v204, v207
	v_lshlrev_b32_e32 v217, 8, v207
	v_lshl_add_u32 v217, v204, 4, v217
	v_and_b32_e32 v204, 1, v206
	v_lshl_add_u32 v217, v204, 3, v217
; #define LAS __attribute__((address_space(3)))
; __device__ __forceinline__ void gla_scan_item(const Ctx& C, int item, LAS unsigned char* lds, int tid) {
;     const int jx = item >> 3, bh = (item & 7) * 4 + (jx >> 3), sl = jx & 7, b = bh >> 2, h = bh & 3;
;     LAS bf16* Aq = (LAS bf16*)lds;
;     LAS bf16* Bc = (LAS bf16*)(lds + 25600);
;     LAS bf16* Kt = (LAS bf16*)(lds + 38400);
;     const int wave = tid >> 6, lane = tid & 63, l15 = lane & 15, quad = lane >> 4;
;     f32x4 S[2] = {(f32x4){0.f, 0.f, 0.f, 0.f}, (f32x4){0.f, 0.f, 0.f, 0.f}};
;     *(LAS u32x4*)(Bc + (tid >> 4) * 200 + (tid & 15) * 8) = (u32x4){0u, 0u, 0u, 0u};
;     u32x4 rq0A, rq1A, rsA, rk0A, rk1A, rvA = (u32x4){0u, 0u, 0u, 0u}; f32x4 rdA;
;     u32x4 rq0B, rq1B, rsB, rk0B, rk1B, rvB = (u32x4){0u, 0u, 0u, 0u}; f32x4 rdB;
	v_add_u32_e32 v217, 0x1e000, v217
	v_bfe_u32 v205, v162, 2, 6
	v_and_b32_e32 v203, 3, v162
	v_lshl_add_u32 v204, v203, 3, 0
	v_lshlrev_b32_e32 v216, 7, v204
	v_bfe_u32 v204, v204, 1, 3
	v_lshrrev_b32_e32 v245, 3, v205
	v_xor_b32_e32 v204, v204, v245
	v_lshl_add_u32 v216, v204, 4, v216
	v_and_b32_e32 v204, 7, v205
	v_lshl_add_u32 v216, v204, 1, v216
	v_add_u32_e32 v216, 0x20100, v216
	v_lshl_add_u32 v204, v203, 3, 1
	v_lshlrev_b32_e32 v215, 7, v204
	v_bfe_u32 v204, v204, 1, 3
	v_lshrrev_b32_e32 v245, 3, v205
	v_xor_b32_e32 v204, v204, v245
	v_lshl_add_u32 v215, v204, 4, v215
	v_and_b32_e32 v204, 7, v205
	v_lshl_add_u32 v215, v204, 1, v215
	v_add_u32_e32 v215, 0x20100, v215
	v_lshl_add_u32 v204, v203, 3, 2
	v_lshlrev_b32_e32 v214, 7, v204
	v_bfe_u32 v204, v204, 1, 3
	v_lshrrev_b32_e32 v245, 3, v205
	v_xor_b32_e32 v204, v204, v245
	v_lshl_add_u32 v214, v204, 4, v214
	v_and_b32_e32 v204, 7, v205
	v_lshl_add_u32 v214, v204, 1, v214
	v_add_u32_e32 v214, 0x20100, v214
	v_lshl_add_u32 v204, v203, 3, 3
	v_lshlrev_b32_e32 v213, 7, v204
	v_bfe_u32 v204, v204, 1, 3
	v_lshrrev_b32_e32 v245, 3, v205
	v_xor_b32_e32 v204, v204, v245
	v_lshl_add_u32 v213, v204, 4, v213
	v_and_b32_e32 v204, 7, v205
	v_lshl_add_u32 v213, v204, 1, v213
	v_add_u32_e32 v213, 0x20100, v213
	v_lshl_add_u32 v204, v203, 3, 4
	v_lshlrev_b32_e32 v212, 7, v204
	v_bfe_u32 v204, v204, 1, 3
	v_lshrrev_b32_e32 v245, 3, v205
	v_xor_b32_e32 v204, v204, v245
	v_lshl_add_u32 v212, v204, 4, v212
	v_and_b32_e32 v204, 7, v205
	v_lshl_add_u32 v212, v204, 1, v212
	v_add_u32_e32 v212, 0x20100, v212
	v_lshl_add_u32 v204, v203, 3, 5
	v_lshlrev_b32_e32 v211, 7, v204
	v_bfe_u32 v204, v204, 1, 3
	v_lshrrev_b32_e32 v245, 3, v205
	v_xor_b32_e32 v204, v204, v245
	v_lshl_add_u32 v211, v204, 4, v211
	v_and_b32_e32 v204, 7, v205
	v_lshl_add_u32 v211, v204, 1, v211
	v_add_u32_e32 v211, 0x20100, v211
	v_lshl_add_u32 v204, v203, 3, 6
	v_lshlrev_b32_e32 v210, 7, v204
	v_bfe_u32 v204, v204, 1, 3
	v_lshrrev_b32_e32 v245, 3, v205
	v_xor_b32_e32 v204, v204, v245
	v_lshl_add_u32 v210, v204, 4, v210
	v_and_b32_e32 v204, 7, v205
	v_lshl_add_u32 v210, v204, 1, v210
	v_add_u32_e32 v210, 0x20100, v210
	v_lshl_add_u32 v204, v203, 3, 7
	v_lshlrev_b32_e32 v209, 7, v204
	v_bfe_u32 v204, v204, 1, 3
	v_lshrrev_b32_e32 v245, 3, v205
	v_xor_b32_e32 v204, v204, v245
	v_lshl_add_u32 v209, v204, 4, v209
	v_and_b32_e32 v204, 7, v205
	v_lshl_add_u32 v209, v204, 1, v209
	v_add_u32_e32 v209, 0x20100, v209
	v_bfe_u32 v205, v162, 2, 6
	v_and_b32_e32 v204, 3, v162
	v_lshlrev_b32_e32 v250, 14, v205
	v_lshl_add_u32 v250, v204, 4, v250
	v_and_b32_e32 v205, 3, v163
	v_lshlrev_b32_e32 v249, 7, v205
	v_lshl_add_u32 v249, v206, 4, v249
	v_lshlrev_b32_e32 v247, 15, v205
	v_lshl_add_u32 v247, v206, 12, v247
	v_lshl_add_u32 v247, v207, 2, v247
	v_add_u32_e32 v246, 0x4000, v247
	v_lshlrev_b32_e32 v245, 4, v162
	v_add_u32_e32 v245, 0x1e000, v245
	v_mov_b32_e32 v188, 0
	v_mov_b32_e32 v189, 0
	v_mov_b32_e32 v190, 0
	v_mov_b32_e32 v191, 0
	s_cmp_gt_u32 s32, 3
	s_cbranch_scc1 .Lp3S_entry
.Lp3O_entry:
	s_mov_b32 s3, s2
.Lp3O_item:
	s_lshr_b32 s4, s3, 3
	s_and_b32 s41, s4, 7
	s_lshr_b32 s5, s4, 3
	s_and_b32 s37, s3, 7
	s_lshl_b32 s37, s37, 2
	s_add_i32 s37, s37, s5
	s_lshr_b32 s39, s37, 2
	s_and_b32 s40, s37, 3
	s_add_u32 s8, s94, 0x1d800000
	s_addc_u32 s9, s95, 0
	s_lshl_b32 s31, s39, 21
	s_add_u32 s8, s8, s31
	s_addc_u32 s9, s9, 0
	s_lshl_b32 s31, s40, 8
	s_add_u32 s8, s8, s31
	s_addc_u32 s9, s9, 0
	s_add_u32 s10, s94, 0x2f00000
	s_addc_u32 s11, s95, 0
	s_lshl_b32 s31, s37, 18
	s_add_u32 s10, s10, s31
	s_addc_u32 s11, s11, 0
	s_add_u32 s12, s94, 0x3700000
	s_addc_u32 s13, s95, 0
	s_lshl_b32 s31, s37, 19
	s_add_u32 s12, s12, s31
	s_addc_u32 s13, s13, 0
	s_add_u32 s14, s94, 0xd402000
	s_addc_u32 s15, s95, 0
	s_lshl_b32 s31, s39, 25
	s_add_u32 s14, s14, s31
	s_addc_u32 s15, s15, 0
	s_lshl_b32 s31, s40, 9
	s_add_u32 s14, s14, s31
	s_addc_u32 s15, s15, 0
	s_lshl_b32 s31, s41, 6
	s_add_u32 s14, s14, s31
	s_addc_u32 s15, s15, 0
	s_add_u32 s18, s6, 0x0
	s_addc_u32 s19, s7, 0
	s_lshl_b32 s31, s39, 22
	s_add_u32 s18, s18, s31
	s_addc_u32 s19, s19, 0
	s_lshl_b32 s31, s40, 9
	s_add_u32 s18, s18, s31
	s_addc_u32 s19, s19, 0
	s_lshl_b32 s31, s41, 6
	s_add_u32 s18, s18, s31
	s_addc_u32 s19, s19, 0
	ds_write_b128 v245, v[188:191]
	s_mov_b32 m0, s46
	s_nop 0
	global_load_lds_dwordx4 v255, s[8:9]
	s_add_i32 m0, s46, 0x400
	s_nop 0
	global_load_lds_dwordx4 v254, s[8:9]
	s_mov_b32 m0, s47
	s_nop 0
	global_load_lds_dwordx4 v253, s[10:11]
	s_mov_b32 m0, s48
	s_nop 0
	global_load_lds_dwordx4 v252, s[12:13]
	s_add_i32 m0, s48, 0x400
	s_nop 0
	global_load_lds_dwordx4 v251, s[12:13]
	s_add_u32 s8, s8, 0x10000
	s_addc_u32 s9, s9, 0
	s_add_u32 s10, s10, 0x2000
	s_addc_u32 s11, s11, 0
	s_add_u32 s12, s12, 0x4000
	s_addc_u32 s13, s13, 0
	s_add_i32 m0, s46, 0xa000
	s_nop 0
	global_load_lds_dwordx4 v255, s[8:9]
	s_add_i32 m0, s46, 0xa400
	s_nop 0
	global_load_lds_dwordx4 v254, s[8:9]
	s_add_i32 m0, s47, 0xa000
	s_nop 0
	global_load_lds_dwordx4 v253, s[10:11]
	s_add_i32 m0, s48, 0xa000
	s_nop 0
	global_load_lds_dwordx4 v252, s[12:13]
	s_add_i32 m0, s48, 0xa400
	s_nop 0
	global_load_lds_dwordx4 v251, s[12:13]
	s_add_u32 s8, s8, 0x10000
	s_addc_u32 s9, s9, 0
	s_add_u32 s10, s10, 0x2000
	s_addc_u32 s11, s11, 0
	s_add_u32 s12, s12, 0x4000
	s_addc_u32 s13, s13, 0
	global_load_dwordx4 v[8:11], v250, s[14:15]
	s_add_u32 s14, s14, 0x100000
	s_addc_u32 s15, s15, 0
	global_load_dwordx4 v[20:23], v250, s[14:15]
	s_add_u32 s14, s14, 0x100000
	s_addc_u32 s15, s15, 0
	global_load_dwordx4 v[32:35], v250, s[14:15]
	s_add_u32 s14, s14, 0x100000
	s_addc_u32 s15, s15, 0
	s_waitcnt vmcnt(0)
	ds_write_b16 v216, v8 offset:0
	ds_write_b16_d16_hi v215, v8 offset:0
	ds_write_b16 v214, v9 offset:0
	ds_write_b16_d16_hi v213, v9 offset:0
	ds_write_b16 v212, v10 offset:0
	ds_write_b16_d16_hi v211, v10 offset:0
	ds_write_b16 v210, v11 offset:0
	ds_write_b16_d16_hi v209, v11 offset:0
	s_mov_b32 s33, 0
	s_waitcnt lgkmcnt(0)
	s_barrier
.Lp3O_loop:
	ds_read_b128 v[44:47], v244 offset:0
	ds_read_b128 v[68:71], v226 offset:0
	ds_read_b128 v[92:95], v226 offset:4096
	ds_read_b128 v[48:51], v243 offset:0
	ds_read_b128 v[72:75], v225 offset:0
	ds_read_b128 v[96:99], v225 offset:4096
	ds_read_b128 v[52:55], v242 offset:0
	ds_read_b128 v[76:79], v224 offset:0
	ds_read_b128 v[100:103], v224 offset:4096
	ds_read_b128 v[56:59], v241 offset:0
	ds_read_b128 v[80:83], v223 offset:0
	ds_read_b128 v[104:107], v223 offset:4096
	ds_read_b128 v[60:63], v234 offset:0
	ds_read_b128 v[84:87], v222 offset:0
	ds_read_b128 v[108:111], v222 offset:2048
	ds_read_b128 v[64:67], v233 offset:0
	ds_read_b128 v[88:91], v221 offset:0
	ds_read_b128 v[112:115], v221 offset:2048
	s_waitcnt vmcnt(10)
	s_add_i32 m0, s46, 0x14000
	s_nop 0
	global_load_lds_dwordx4 v255, s[8:9]
	s_add_i32 m0, s46, 0x14400
	s_nop 0
	global_load_lds_dwordx4 v254, s[8:9]
	s_add_i32 m0, s47, 0x14000
	s_nop 0
	global_load_lds_dwordx4 v253, s[10:11]
	s_add_i32 m0, s48, 0x14000
	s_nop 0
	global_load_lds_dwordx4 v252, s[12:13]
	s_add_i32 m0, s48, 0x14400
	s_nop 0
	global_load_lds_dwordx4 v251, s[12:13]
	s_cmp_lt_u32 s33, 29
	s_cselect_b32 s43, 0x10000, 0
	s_add_u32 s8, s8, s43
	s_addc_u32 s9, s9, 0
	s_cmp_lt_u32 s33, 29
	s_cselect_b32 s43, 0x2000, 0
	s_add_u32 s10, s10, s43
	s_addc_u32 s11, s11, 0
	s_cmp_lt_u32 s33, 29
	s_cselect_b32 s43, 0x4000, 0
	s_add_u32 s12, s12, s43
	s_addc_u32 s13, s13, 0
	s_waitcnt lgkmcnt(15)
	v_mfma_f32_16x16x32_bf16 v[168:171], v[68:71], v[44:47], 0
	v_mfma_f32_16x16x32_bf16 v[172:175], v[92:95], v[44:47], 0
	s_waitcnt lgkmcnt(12)
	v_mfma_f32_16x16x32_bf16 v[168:171], v[72:75], v[48:51], v[168:171]
	v_mfma_f32_16x16x32_bf16 v[172:175], v[96:99], v[48:51], v[172:175]
	s_waitcnt lgkmcnt(9)
	v_mfma_f32_16x16x32_bf16 v[168:171], v[76:79], v[52:55], v[168:171]
	v_mfma_f32_16x16x32_bf16 v[172:175], v[100:103], v[52:55], v[172:175]
	s_waitcnt lgkmcnt(6)
	v_mfma_f32_16x16x32_bf16 v[168:171], v[80:83], v[56:59], v[168:171]
	v_mfma_f32_16x16x32_bf16 v[172:175], v[104:107], v[56:59], v[172:175]
	s_waitcnt lgkmcnt(3)
	v_mfma_f32_16x16x32_bf16 v[168:171], v[84:87], v[60:63], v[168:171]
	v_mfma_f32_16x16x32_bf16 v[172:175], v[108:111], v[60:63], v[172:175]
	s_waitcnt lgkmcnt(0)
	v_mfma_f32_16x16x32_bf16 v[168:171], v[88:91], v[64:67], v[168:171]
	v_mfma_f32_16x16x32_bf16 v[172:175], v[112:115], v[64:67], v[172:175]
	ds_write_b16 v216, v20 offset:12288
	ds_write_b16_d16_hi v215, v20 offset:12288
	ds_write_b16 v214, v21 offset:12288
	ds_write_b16_d16_hi v213, v21 offset:12288
	ds_write_b16 v212, v22 offset:12288
	ds_write_b16_d16_hi v211, v22 offset:12288
	ds_write_b16 v210, v23 offset:12288
	ds_write_b16_d16_hi v209, v23 offset:12288
	global_load_dwordx4 v[8:11], v250, s[14:15]
	s_cmp_lt_u32 s33, 28
	s_cselect_b32 s43, 0x100000, 0
	s_add_u32 s14, s14, s43
	s_addc_u32 s15, s15, 0
	s_nop 7
	v_cvt_pk_bf16_f32 v184, v168, v169
	v_cvt_pk_bf16_f32 v185, v170, v171
	v_cvt_pk_bf16_f32 v186, v172, v173
	v_cvt_pk_bf16_f32 v187, v174, v175
	global_store_dwordx2 v248, v[184:185], s[18:19]
	global_store_dwordx2 v248, v[186:187], s[18:19] offset:32
	s_add_u32 s18, s18, 0x20000
	s_addc_u32 s19, s19, 0
	s_add_i32 s33, s33, 1
	s_waitcnt vmcnt(11)
	s_waitcnt lgkmcnt(0)
	s_barrier
	ds_read_b128 v[44:47], v244 offset:40960
	ds_read_b128 v[68:71], v226 offset:12544
	ds_read_b128 v[92:95], v226 offset:16640
	ds_read_b128 v[48:51], v243 offset:40960
	ds_read_b128 v[72:75], v225 offset:12544
	ds_read_b128 v[96:99], v225 offset:16640
	ds_read_b128 v[52:55], v242 offset:40960
	ds_read_b128 v[76:79], v224 offset:12544
	ds_read_b128 v[100:103], v224 offset:16640
	ds_read_b128 v[56:59], v241 offset:40960
	ds_read_b128 v[80:83], v223 offset:12544
	ds_read_b128 v[104:107], v223 offset:16640
	ds_read_b128 v[60:63], v234 offset:40960
	ds_read_b128 v[84:87], v222 offset:12288
	ds_read_b128 v[108:111], v222 offset:14336
	ds_read_b128 v[64:67], v233 offset:40960
	ds_read_b128 v[88:91], v221 offset:12288
	ds_read_b128 v[112:115], v221 offset:14336
	s_waitcnt vmcnt(10)
	s_mov_b32 m0, s46
	s_nop 0
	global_load_lds_dwordx4 v255, s[8:9]
	s_add_i32 m0, s46, 0x400
	s_nop 0
	global_load_lds_dwordx4 v254, s[8:9]
	s_mov_b32 m0, s47
	s_nop 0
	global_load_lds_dwordx4 v253, s[10:11]
	s_mov_b32 m0, s48
	s_nop 0
	global_load_lds_dwordx4 v252, s[12:13]
	s_add_i32 m0, s48, 0x400
	s_nop 0
	global_load_lds_dwordx4 v251, s[12:13]
	s_cmp_lt_u32 s33, 29
	s_cselect_b32 s43, 0x10000, 0
	s_add_u32 s8, s8, s43
	s_addc_u32 s9, s9, 0
	s_cmp_lt_u32 s33, 29
	s_cselect_b32 s43, 0x2000, 0
	s_add_u32 s10, s10, s43
	s_addc_u32 s11, s11, 0
	s_cmp_lt_u32 s33, 29
	s_cselect_b32 s43, 0x4000, 0
	s_add_u32 s12, s12, s43
	s_addc_u32 s13, s13, 0
	s_waitcnt lgkmcnt(15)
	v_mfma_f32_16x16x32_bf16 v[168:171], v[68:71], v[44:47], 0
	v_mfma_f32_16x16x32_bf16 v[172:175], v[92:95], v[44:47], 0
	s_waitcnt lgkmcnt(12)
	v_mfma_f32_16x16x32_bf16 v[168:171], v[72:75], v[48:51], v[168:171]
	v_mfma_f32_16x16x32_bf16 v[172:175], v[96:99], v[48:51], v[172:175]
	s_waitcnt lgkmcnt(9)
	v_mfma_f32_16x16x32_bf16 v[168:171], v[76:79], v[52:55], v[168:171]
	v_mfma_f32_16x16x32_bf16 v[172:175], v[100:103], v[52:55], v[172:175]
	s_waitcnt lgkmcnt(6)
	v_mfma_f32_16x16x32_bf16 v[168:171], v[80:83], v[56:59], v[168:171]
	v_mfma_f32_16x16x32_bf16 v[172:175], v[104:107], v[56:59], v[172:175]
	s_waitcnt lgkmcnt(3)
	v_mfma_f32_16x16x32_bf16 v[168:171], v[84:87], v[60:63], v[168:171]
	v_mfma_f32_16x16x32_bf16 v[172:175], v[108:111], v[60:63], v[172:175]
	s_waitcnt lgkmcnt(0)
	v_mfma_f32_16x16x32_bf16 v[168:171], v[88:91], v[64:67], v[168:171]
	v_mfma_f32_16x16x32_bf16 v[172:175], v[112:115], v[64:67], v[172:175]
	ds_write_b16 v216, v32 offset:0
	ds_write_b16_d16_hi v215, v32 offset:0
	ds_write_b16 v214, v33 offset:0
	ds_write_b16_d16_hi v213, v33 offset:0
	ds_write_b16 v212, v34 offset:0
	ds_write_b16_d16_hi v211, v34 offset:0
	ds_write_b16 v210, v35 offset:0
	ds_write_b16_d16_hi v209, v35 offset:0
	global_load_dwordx4 v[20:23], v250, s[14:15]
	s_cmp_lt_u32 s33, 28
	s_cselect_b32 s43, 0x100000, 0
	s_add_u32 s14, s14, s43
	s_addc_u32 s15, s15, 0
	s_nop 7
	v_cvt_pk_bf16_f32 v184, v168, v169
	v_cvt_pk_bf16_f32 v185, v170, v171
	v_cvt_pk_bf16_f32 v186, v172, v173
	v_cvt_pk_bf16_f32 v187, v174, v175
	global_store_dwordx2 v248, v[184:185], s[18:19]
	global_store_dwordx2 v248, v[186:187], s[18:19] offset:32
	s_add_u32 s18, s18, 0x20000
	s_addc_u32 s19, s19, 0
	s_add_i32 s33, s33, 1
	s_waitcnt vmcnt(11)
	s_waitcnt lgkmcnt(0)
	s_barrier
	ds_read_b128 v[44:47], v240 offset:0
	ds_read_b128 v[68:71], v226 offset:0
	ds_read_b128 v[92:95], v226 offset:4096
	ds_read_b128 v[48:51], v239 offset:0
	ds_read_b128 v[72:75], v225 offset:0
	ds_read_b128 v[96:99], v225 offset:4096
	ds_read_b128 v[52:55], v238 offset:0
	ds_read_b128 v[76:79], v224 offset:0
	ds_read_b128 v[100:103], v224 offset:4096
	ds_read_b128 v[56:59], v235 offset:0
	ds_read_b128 v[80:83], v223 offset:0
	ds_read_b128 v[104:107], v223 offset:4096
	ds_read_b128 v[60:63], v232 offset:0
	ds_read_b128 v[84:87], v222 offset:0
	ds_read_b128 v[108:111], v222 offset:2048
	ds_read_b128 v[64:67], v231 offset:0
	ds_read_b128 v[88:91], v221 offset:0
	ds_read_b128 v[112:115], v221 offset:2048
	s_waitcnt vmcnt(10)
	s_add_i32 m0, s46, 0xa000
	s_nop 0
	global_load_lds_dwordx4 v255, s[8:9]
	s_add_i32 m0, s46, 0xa400
	s_nop 0
	global_load_lds_dwordx4 v254, s[8:9]
	s_add_i32 m0, s47, 0xa000
	s_nop 0
	global_load_lds_dwordx4 v253, s[10:11]
	s_add_i32 m0, s48, 0xa000
	s_nop 0
	global_load_lds_dwordx4 v252, s[12:13]
	s_add_i32 m0, s48, 0xa400
	s_nop 0
	global_load_lds_dwordx4 v251, s[12:13]
	s_cmp_lt_u32 s33, 29
	s_cselect_b32 s43, 0x10000, 0
	s_add_u32 s8, s8, s43
	s_addc_u32 s9, s9, 0
	s_cmp_lt_u32 s33, 29
	s_cselect_b32 s43, 0x2000, 0
	s_add_u32 s10, s10, s43
	s_addc_u32 s11, s11, 0
	s_cmp_lt_u32 s33, 29
	s_cselect_b32 s43, 0x4000, 0
	s_add_u32 s12, s12, s43
	s_addc_u32 s13, s13, 0
	s_waitcnt lgkmcnt(15)
	v_mfma_f32_16x16x32_bf16 v[168:171], v[68:71], v[44:47], 0
	v_mfma_f32_16x16x32_bf16 v[172:175], v[92:95], v[44:47], 0
	s_waitcnt lgkmcnt(12)
	v_mfma_f32_16x16x32_bf16 v[168:171], v[72:75], v[48:51], v[168:171]
	v_mfma_f32_16x16x32_bf16 v[172:175], v[96:99], v[48:51], v[172:175]
	s_waitcnt lgkmcnt(9)
	v_mfma_f32_16x16x32_bf16 v[168:171], v[76:79], v[52:55], v[168:171]
	v_mfma_f32_16x16x32_bf16 v[172:175], v[100:103], v[52:55], v[172:175]
	s_waitcnt lgkmcnt(6)
	v_mfma_f32_16x16x32_bf16 v[168:171], v[80:83], v[56:59], v[168:171]
	v_mfma_f32_16x16x32_bf16 v[172:175], v[104:107], v[56:59], v[172:175]
	s_waitcnt lgkmcnt(3)
	v_mfma_f32_16x16x32_bf16 v[168:171], v[84:87], v[60:63], v[168:171]
	v_mfma_f32_16x16x32_bf16 v[172:175], v[108:111], v[60:63], v[172:175]
	s_waitcnt lgkmcnt(0)
	v_mfma_f32_16x16x32_bf16 v[168:171], v[88:91], v[64:67], v[168:171]
	v_mfma_f32_16x16x32_bf16 v[172:175], v[112:115], v[64:67], v[172:175]
	ds_write_b16 v216, v8 offset:12288
	ds_write_b16_d16_hi v215, v8 offset:12288
	ds_write_b16 v214, v9 offset:12288
	ds_write_b16_d16_hi v213, v9 offset:12288
	ds_write_b16 v212, v10 offset:12288
	ds_write_b16_d16_hi v211, v10 offset:12288
	ds_write_b16 v210, v11 offset:12288
	ds_write_b16_d16_hi v209, v11 offset:12288
	global_load_dwordx4 v[32:35], v250, s[14:15]
	s_cmp_lt_u32 s33, 28
	s_cselect_b32 s43, 0x100000, 0
	s_add_u32 s14, s14, s43
	s_addc_u32 s15, s15, 0
	s_nop 7
	v_cvt_pk_bf16_f32 v184, v168, v169
	v_cvt_pk_bf16_f32 v185, v170, v171
	v_cvt_pk_bf16_f32 v186, v172, v173
	v_cvt_pk_bf16_f32 v187, v174, v175
	global_store_dwordx2 v248, v[184:185], s[18:19]
	global_store_dwordx2 v248, v[186:187], s[18:19] offset:32
	s_add_u32 s18, s18, 0x20000
	s_addc_u32 s19, s19, 0
	s_add_i32 s33, s33, 1
	s_waitcnt vmcnt(11)
	s_waitcnt lgkmcnt(0)
	s_barrier
	ds_read_b128 v[44:47], v244 offset:0
	ds_read_b128 v[68:71], v226 offset:12544
	ds_read_b128 v[92:95], v226 offset:16640
	ds_read_b128 v[48:51], v243 offset:0
	ds_read_b128 v[72:75], v225 offset:12544
	ds_read_b128 v[96:99], v225 offset:16640
	ds_read_b128 v[52:55], v242 offset:0
	ds_read_b128 v[76:79], v224 offset:12544
	ds_read_b128 v[100:103], v224 offset:16640
	ds_read_b128 v[56:59], v241 offset:0
	ds_read_b128 v[80:83], v223 offset:12544
	ds_read_b128 v[104:107], v223 offset:16640
	ds_read_b128 v[60:63], v234 offset:0
	ds_read_b128 v[84:87], v222 offset:12288
	ds_read_b128 v[108:111], v222 offset:14336
	ds_read_b128 v[64:67], v233 offset:0
	ds_read_b128 v[88:91], v221 offset:12288
	ds_read_b128 v[112:115], v221 offset:14336
	s_waitcnt vmcnt(10)
	s_add_i32 m0, s46, 0x14000
	s_nop 0
	global_load_lds_dwordx4 v255, s[8:9]
	s_add_i32 m0, s46, 0x14400
	s_nop 0
	global_load_lds_dwordx4 v254, s[8:9]
	s_add_i32 m0, s47, 0x14000
	s_nop 0
	global_load_lds_dwordx4 v253, s[10:11]
	s_add_i32 m0, s48, 0x14000
	s_nop 0
	global_load_lds_dwordx4 v252, s[12:13]
	s_add_i32 m0, s48, 0x14400
	s_nop 0
	global_load_lds_dwordx4 v251, s[12:13]
	s_cmp_lt_u32 s33, 29
	s_cselect_b32 s43, 0x10000, 0
	s_add_u32 s8, s8, s43
	s_addc_u32 s9, s9, 0
	s_cmp_lt_u32 s33, 29
	s_cselect_b32 s43, 0x2000, 0
	s_add_u32 s10, s10, s43
	s_addc_u32 s11, s11, 0
	s_cmp_lt_u32 s33, 29
	s_cselect_b32 s43, 0x4000, 0
	s_add_u32 s12, s12, s43
	s_addc_u32 s13, s13, 0
	s_waitcnt lgkmcnt(15)
	v_mfma_f32_16x16x32_bf16 v[168:171], v[68:71], v[44:47], 0
	v_mfma_f32_16x16x32_bf16 v[172:175], v[92:95], v[44:47], 0
	s_waitcnt lgkmcnt(12)
	v_mfma_f32_16x16x32_bf16 v[168:171], v[72:75], v[48:51], v[168:171]
	v_mfma_f32_16x16x32_bf16 v[172:175], v[96:99], v[48:51], v[172:175]
	s_waitcnt lgkmcnt(9)
	v_mfma_f32_16x16x32_bf16 v[168:171], v[76:79], v[52:55], v[168:171]
	v_mfma_f32_16x16x32_bf16 v[172:175], v[100:103], v[52:55], v[172:175]
	s_waitcnt lgkmcnt(6)
	v_mfma_f32_16x16x32_bf16 v[168:171], v[80:83], v[56:59], v[168:171]
	v_mfma_f32_16x16x32_bf16 v[172:175], v[104:107], v[56:59], v[172:175]
	s_waitcnt lgkmcnt(3)
	v_mfma_f32_16x16x32_bf16 v[168:171], v[84:87], v[60:63], v[168:171]
	v_mfma_f32_16x16x32_bf16 v[172:175], v[108:111], v[60:63], v[172:175]
	s_waitcnt lgkmcnt(0)
	v_mfma_f32_16x16x32_bf16 v[168:171], v[88:91], v[64:67], v[168:171]
	v_mfma_f32_16x16x32_bf16 v[172:175], v[112:115], v[64:67], v[172:175]
	ds_write_b16 v216, v20 offset:0
	ds_write_b16_d16_hi v215, v20 offset:0
	ds_write_b16 v214, v21 offset:0
	ds_write_b16_d16_hi v213, v21 offset:0
	ds_write_b16 v212, v22 offset:0
	ds_write_b16_d16_hi v211, v22 offset:0
	ds_write_b16 v210, v23 offset:0
	ds_write_b16_d16_hi v209, v23 offset:0
	global_load_dwordx4 v[8:11], v250, s[14:15]
	s_cmp_lt_u32 s33, 28
	s_cselect_b32 s43, 0x100000, 0
	s_add_u32 s14, s14, s43
	s_addc_u32 s15, s15, 0
	s_nop 7
	v_cvt_pk_bf16_f32 v184, v168, v169
	v_cvt_pk_bf16_f32 v185, v170, v171
	v_cvt_pk_bf16_f32 v186, v172, v173
	v_cvt_pk_bf16_f32 v187, v174, v175
	global_store_dwordx2 v248, v[184:185], s[18:19]
	global_store_dwordx2 v248, v[186:187], s[18:19] offset:32
	s_add_u32 s18, s18, 0x20000
	s_addc_u32 s19, s19, 0
	s_add_i32 s33, s33, 1
	s_waitcnt vmcnt(11)
	s_waitcnt lgkmcnt(0)
	s_barrier
	ds_read_b128 v[44:47], v244 offset:40960
	ds_read_b128 v[68:71], v226 offset:0
	ds_read_b128 v[92:95], v226 offset:4096
	ds_read_b128 v[48:51], v243 offset:40960
	ds_read_b128 v[72:75], v225 offset:0
	ds_read_b128 v[96:99], v225 offset:4096
	ds_read_b128 v[52:55], v242 offset:40960
	ds_read_b128 v[76:79], v224 offset:0
	ds_read_b128 v[100:103], v224 offset:4096
	ds_read_b128 v[56:59], v241 offset:40960
	ds_read_b128 v[80:83], v223 offset:0
	ds_read_b128 v[104:107], v223 offset:4096
	ds_read_b128 v[60:63], v234 offset:40960
	ds_read_b128 v[84:87], v222 offset:0
	ds_read_b128 v[108:111], v222 offset:2048
	ds_read_b128 v[64:67], v233 offset:40960
	ds_read_b128 v[88:91], v221 offset:0
	ds_read_b128 v[112:115], v221 offset:2048
	s_waitcnt vmcnt(10)
	s_mov_b32 m0, s46
	s_nop 0
	global_load_lds_dwordx4 v255, s[8:9]
	s_add_i32 m0, s46, 0x400
	s_nop 0
	global_load_lds_dwordx4 v254, s[8:9]
	s_mov_b32 m0, s47
	s_nop 0
	global_load_lds_dwordx4 v253, s[10:11]
	s_mov_b32 m0, s48
	s_nop 0
	global_load_lds_dwordx4 v252, s[12:13]
	s_add_i32 m0, s48, 0x400
	s_nop 0
	global_load_lds_dwordx4 v251, s[12:13]
	s_cmp_lt_u32 s33, 29
	s_cselect_b32 s43, 0x10000, 0
	s_add_u32 s8, s8, s43
	s_addc_u32 s9, s9, 0
	s_cmp_lt_u32 s33, 29
	s_cselect_b32 s43, 0x2000, 0
	s_add_u32 s10, s10, s43
	s_addc_u32 s11, s11, 0
	s_cmp_lt_u32 s33, 29
	s_cselect_b32 s43, 0x4000, 0
	s_add_u32 s12, s12, s43
	s_addc_u32 s13, s13, 0
	s_waitcnt lgkmcnt(15)
	v_mfma_f32_16x16x32_bf16 v[168:171], v[68:71], v[44:47], 0
	v_mfma_f32_16x16x32_bf16 v[172:175], v[92:95], v[44:47], 0
	s_waitcnt lgkmcnt(12)
	v_mfma_f32_16x16x32_bf16 v[168:171], v[72:75], v[48:51], v[168:171]
	v_mfma_f32_16x16x32_bf16 v[172:175], v[96:99], v[48:51], v[172:175]
	s_waitcnt lgkmcnt(9)
	v_mfma_f32_16x16x32_bf16 v[168:171], v[76:79], v[52:55], v[168:171]
	v_mfma_f32_16x16x32_bf16 v[172:175], v[100:103], v[52:55], v[172:175]
	s_waitcnt lgkmcnt(6)
	v_mfma_f32_16x16x32_bf16 v[168:171], v[80:83], v[56:59], v[168:171]
	v_mfma_f32_16x16x32_bf16 v[172:175], v[104:107], v[56:59], v[172:175]
	s_waitcnt lgkmcnt(3)
	v_mfma_f32_16x16x32_bf16 v[168:171], v[84:87], v[60:63], v[168:171]
	v_mfma_f32_16x16x32_bf16 v[172:175], v[108:111], v[60:63], v[172:175]
	s_waitcnt lgkmcnt(0)
	v_mfma_f32_16x16x32_bf16 v[168:171], v[88:91], v[64:67], v[168:171]
	v_mfma_f32_16x16x32_bf16 v[172:175], v[112:115], v[64:67], v[172:175]
	ds_write_b16 v216, v32 offset:12288
	ds_write_b16_d16_hi v215, v32 offset:12288
	ds_write_b16 v214, v33 offset:12288
	ds_write_b16_d16_hi v213, v33 offset:12288
	ds_write_b16 v212, v34 offset:12288
	ds_write_b16_d16_hi v211, v34 offset:12288
	ds_write_b16 v210, v35 offset:12288
	ds_write_b16_d16_hi v209, v35 offset:12288
	global_load_dwordx4 v[20:23], v250, s[14:15]
	s_cmp_lt_u32 s33, 28
	s_cselect_b32 s43, 0x100000, 0
	s_add_u32 s14, s14, s43
	s_addc_u32 s15, s15, 0
	s_nop 7
	v_cvt_pk_bf16_f32 v184, v168, v169
	v_cvt_pk_bf16_f32 v185, v170, v171
	v_cvt_pk_bf16_f32 v186, v172, v173
	v_cvt_pk_bf16_f32 v187, v174, v175
	global_store_dwordx2 v248, v[184:185], s[18:19]
	global_store_dwordx2 v248, v[186:187], s[18:19] offset:32
	s_add_u32 s18, s18, 0x20000
	s_addc_u32 s19, s19, 0
	s_add_i32 s33, s33, 1
	s_waitcnt vmcnt(11)
	s_waitcnt lgkmcnt(0)
	s_barrier
	ds_read_b128 v[44:47], v240 offset:0
	ds_read_b128 v[68:71], v226 offset:12544
	ds_read_b128 v[92:95], v226 offset:16640
	ds_read_b128 v[48:51], v239 offset:0
	ds_read_b128 v[72:75], v225 offset:12544
	ds_read_b128 v[96:99], v225 offset:16640
	ds_read_b128 v[52:55], v238 offset:0
	ds_read_b128 v[76:79], v224 offset:12544
	ds_read_b128 v[100:103], v224 offset:16640
	ds_read_b128 v[56:59], v235 offset:0
	ds_read_b128 v[80:83], v223 offset:12544
	ds_read_b128 v[104:107], v223 offset:16640
	ds_read_b128 v[60:63], v232 offset:0
	ds_read_b128 v[84:87], v222 offset:12288
	ds_read_b128 v[108:111], v222 offset:14336
	ds_read_b128 v[64:67], v231 offset:0
	ds_read_b128 v[88:91], v221 offset:12288
	ds_read_b128 v[112:115], v221 offset:14336
	s_waitcnt vmcnt(10)
	s_add_i32 m0, s46, 0xa000
	s_nop 0
	global_load_lds_dwordx4 v255, s[8:9]
	s_add_i32 m0, s46, 0xa400
	s_nop 0
	global_load_lds_dwordx4 v254, s[8:9]
	s_add_i32 m0, s47, 0xa000
	s_nop 0
	global_load_lds_dwordx4 v253, s[10:11]
	s_add_i32 m0, s48, 0xa000
	s_nop 0
	global_load_lds_dwordx4 v252, s[12:13]
	s_add_i32 m0, s48, 0xa400
	s_nop 0
	global_load_lds_dwordx4 v251, s[12:13]
	s_cmp_lt_u32 s33, 29
	s_cselect_b32 s43, 0x10000, 0
	s_add_u32 s8, s8, s43
	s_addc_u32 s9, s9, 0
	s_cmp_lt_u32 s33, 29
	s_cselect_b32 s43, 0x2000, 0
	s_add_u32 s10, s10, s43
	s_addc_u32 s11, s11, 0
	s_cmp_lt_u32 s33, 29
	s_cselect_b32 s43, 0x4000, 0
	s_add_u32 s12, s12, s43
	s_addc_u32 s13, s13, 0
	s_waitcnt lgkmcnt(15)
	v_mfma_f32_16x16x32_bf16 v[168:171], v[68:71], v[44:47], 0
	v_mfma_f32_16x16x32_bf16 v[172:175], v[92:95], v[44:47], 0
	s_waitcnt lgkmcnt(12)
	v_mfma_f32_16x16x32_bf16 v[168:171], v[72:75], v[48:51], v[168:171]
	v_mfma_f32_16x16x32_bf16 v[172:175], v[96:99], v[48:51], v[172:175]
	s_waitcnt lgkmcnt(9)
	v_mfma_f32_16x16x32_bf16 v[168:171], v[76:79], v[52:55], v[168:171]
	v_mfma_f32_16x16x32_bf16 v[172:175], v[100:103], v[52:55], v[172:175]
	s_waitcnt lgkmcnt(6)
	v_mfma_f32_16x16x32_bf16 v[168:171], v[80:83], v[56:59], v[168:171]
	v_mfma_f32_16x16x32_bf16 v[172:175], v[104:107], v[56:59], v[172:175]
	s_waitcnt lgkmcnt(3)
	v_mfma_f32_16x16x32_bf16 v[168:171], v[84:87], v[60:63], v[168:171]
	v_mfma_f32_16x16x32_bf16 v[172:175], v[108:111], v[60:63], v[172:175]
	s_waitcnt lgkmcnt(0)
	v_mfma_f32_16x16x32_bf16 v[168:171], v[88:91], v[64:67], v[168:171]
	v_mfma_f32_16x16x32_bf16 v[172:175], v[112:115], v[64:67], v[172:175]
	ds_write_b16 v216, v8 offset:0
	ds_write_b16_d16_hi v215, v8 offset:0
	ds_write_b16 v214, v9 offset:0
	ds_write_b16_d16_hi v213, v9 offset:0
	ds_write_b16 v212, v10 offset:0
	ds_write_b16_d16_hi v211, v10 offset:0
	ds_write_b16 v210, v11 offset:0
	ds_write_b16_d16_hi v209, v11 offset:0
	global_load_dwordx4 v[32:35], v250, s[14:15]
	s_cmp_lt_u32 s33, 28
	s_cselect_b32 s43, 0x100000, 0
	s_add_u32 s14, s14, s43
	s_addc_u32 s15, s15, 0
	s_nop 7
	v_cvt_pk_bf16_f32 v184, v168, v169
	v_cvt_pk_bf16_f32 v185, v170, v171
	v_cvt_pk_bf16_f32 v186, v172, v173
	v_cvt_pk_bf16_f32 v187, v174, v175
	global_store_dwordx2 v248, v[184:185], s[18:19]
	global_store_dwordx2 v248, v[186:187], s[18:19] offset:32
	s_add_u32 s18, s18, 0x20000
	s_addc_u32 s19, s19, 0
	s_add_i32 s33, s33, 1
	s_waitcnt vmcnt(11)
	s_waitcnt lgkmcnt(0)
	s_barrier
; __device__ __forceinline__ void gla_scan_item(const Ctx& C, int item, LAS unsigned char* lds, int tid) {
;     ...
;     SCAN_LOAD(A, 0); SCAN_LOAD(B, 1);
; #pragma unroll
;     for (int n = 0; n < 32; n += 2) { SCAN_STEP(A, n); SCAN_STEP(B, n + 1); }
	s_cmp_lt_u32 s33, 30
	s_cbranch_scc1 .Lp3O_loop
	ds_read_b128 v[44:47], v244 offset:0
	ds_read_b128 v[68:71], v226 offset:0
	ds_read_b128 v[92:95], v226 offset:4096
	ds_read_b128 v[48:51], v243 offset:0
	ds_read_b128 v[72:75], v225 offset:0
	ds_read_b128 v[96:99], v225 offset:4096
	ds_read_b128 v[52:55], v242 offset:0
	ds_read_b128 v[76:79], v224 offset:0
	ds_read_b128 v[100:103], v224 offset:4096
	ds_read_b128 v[56:59], v241 offset:0
	ds_read_b128 v[80:83], v223 offset:0
	ds_read_b128 v[104:107], v223 offset:4096
	ds_read_b128 v[60:63], v234 offset:0
	ds_read_b128 v[84:87], v222 offset:0
	ds_read_b128 v[108:111], v222 offset:2048
	ds_read_b128 v[64:67], v233 offset:0
	ds_read_b128 v[88:91], v221 offset:0
	ds_read_b128 v[112:115], v221 offset:2048
	s_waitcnt vmcnt(10)
	s_add_i32 m0, s46, 0x14000
	s_nop 0
	global_load_lds_dwordx4 v255, s[8:9]
	s_add_i32 m0, s46, 0x14400
	s_nop 0
	global_load_lds_dwordx4 v254, s[8:9]
	s_add_i32 m0, s47, 0x14000
	s_nop 0
	global_load_lds_dwordx4 v253, s[10:11]
	s_add_i32 m0, s48, 0x14000
	s_nop 0
	global_load_lds_dwordx4 v252, s[12:13]
	s_add_i32 m0, s48, 0x14400
	s_nop 0
	global_load_lds_dwordx4 v251, s[12:13]
	s_cmp_lt_u32 s33, 29
	s_cselect_b32 s43, 0x10000, 0
	s_add_u32 s8, s8, s43
	s_addc_u32 s9, s9, 0
	s_cmp_lt_u32 s33, 29
	s_cselect_b32 s43, 0x2000, 0
	s_add_u32 s10, s10, s43
	s_addc_u32 s11, s11, 0
	s_cmp_lt_u32 s33, 29
	s_cselect_b32 s43, 0x4000, 0
	s_add_u32 s12, s12, s43
	s_addc_u32 s13, s13, 0
	s_waitcnt lgkmcnt(15)
	v_mfma_f32_16x16x32_bf16 v[168:171], v[68:71], v[44:47], 0
	v_mfma_f32_16x16x32_bf16 v[172:175], v[92:95], v[44:47], 0
	s_waitcnt lgkmcnt(12)
	v_mfma_f32_16x16x32_bf16 v[168:171], v[72:75], v[48:51], v[168:171]
	v_mfma_f32_16x16x32_bf16 v[172:175], v[96:99], v[48:51], v[172:175]
	s_waitcnt lgkmcnt(9)
	v_mfma_f32_16x16x32_bf16 v[168:171], v[76:79], v[52:55], v[168:171]
	v_mfma_f32_16x16x32_bf16 v[172:175], v[100:103], v[52:55], v[172:175]
	s_waitcnt lgkmcnt(6)
	v_mfma_f32_16x16x32_bf16 v[168:171], v[80:83], v[56:59], v[168:171]
	v_mfma_f32_16x16x32_bf16 v[172:175], v[104:107], v[56:59], v[172:175]
	s_waitcnt lgkmcnt(3)
	v_mfma_f32_16x16x32_bf16 v[168:171], v[84:87], v[60:63], v[168:171]
	v_mfma_f32_16x16x32_bf16 v[172:175], v[108:111], v[60:63], v[172:175]
	s_waitcnt lgkmcnt(0)
	v_mfma_f32_16x16x32_bf16 v[168:171], v[88:91], v[64:67], v[168:171]
	v_mfma_f32_16x16x32_bf16 v[172:175], v[112:115], v[64:67], v[172:175]
	ds_write_b16 v216, v20 offset:12288
	ds_write_b16_d16_hi v215, v20 offset:12288
	ds_write_b16 v214, v21 offset:12288
	ds_write_b16_d16_hi v213, v21 offset:12288
	ds_write_b16 v212, v22 offset:12288
	ds_write_b16_d16_hi v211, v22 offset:12288
	ds_write_b16 v210, v23 offset:12288
	ds_write_b16_d16_hi v209, v23 offset:12288
	global_load_dwordx4 v[8:11], v250, s[14:15]
	s_cmp_lt_u32 s33, 28
	s_cselect_b32 s43, 0x100000, 0
	s_add_u32 s14, s14, s43
	s_addc_u32 s15, s15, 0
	s_nop 7
	v_cvt_pk_bf16_f32 v184, v168, v169
	v_cvt_pk_bf16_f32 v185, v170, v171
	v_cvt_pk_bf16_f32 v186, v172, v173
	v_cvt_pk_bf16_f32 v187, v174, v175
	global_store_dwordx2 v248, v[184:185], s[18:19]
	global_store_dwordx2 v248, v[186:187], s[18:19] offset:32
	s_add_u32 s18, s18, 0x20000
	s_addc_u32 s19, s19, 0
	s_add_i32 s33, s33, 1
	s_waitcnt vmcnt(11)
	s_waitcnt lgkmcnt(0)
	s_barrier
	ds_read_b128 v[44:47], v244 offset:40960
	ds_read_b128 v[68:71], v226 offset:12544
	ds_read_b128 v[92:95], v226 offset:16640
	ds_read_b128 v[48:51], v243 offset:40960
	ds_read_b128 v[72:75], v225 offset:12544
	ds_read_b128 v[96:99], v225 offset:16640
	ds_read_b128 v[52:55], v242 offset:40960
	ds_read_b128 v[76:79], v224 offset:12544
	ds_read_b128 v[100:103], v224 offset:16640
	ds_read_b128 v[56:59], v241 offset:40960
	ds_read_b128 v[80:83], v223 offset:12544
	ds_read_b128 v[104:107], v223 offset:16640
	ds_read_b128 v[60:63], v234 offset:40960
	ds_read_b128 v[84:87], v222 offset:12288
	ds_read_b128 v[108:111], v222 offset:14336
	ds_read_b128 v[64:67], v233 offset:40960
	ds_read_b128 v[88:91], v221 offset:12288
	ds_read_b128 v[112:115], v221 offset:14336
	s_waitcnt vmcnt(10)
	s_mov_b32 m0, s46
	s_nop 0
	global_load_lds_dwordx4 v255, s[8:9]
	s_add_i32 m0, s46, 0x400
	s_nop 0
	global_load_lds_dwordx4 v254, s[8:9]
	s_mov_b32 m0, s47
	s_nop 0
	global_load_lds_dwordx4 v253, s[10:11]
	s_mov_b32 m0, s48
	s_nop 0
	global_load_lds_dwordx4 v252, s[12:13]
	s_add_i32 m0, s48, 0x400
	s_nop 0
	global_load_lds_dwordx4 v251, s[12:13]
	s_cmp_lt_u32 s33, 29
	s_cselect_b32 s43, 0x10000, 0
	s_add_u32 s8, s8, s43
	s_addc_u32 s9, s9, 0
	s_cmp_lt_u32 s33, 29
	s_cselect_b32 s43, 0x2000, 0
	s_add_u32 s10, s10, s43
	s_addc_u32 s11, s11, 0
	s_cmp_lt_u32 s33, 29
	s_cselect_b32 s43, 0x4000, 0
	s_add_u32 s12, s12, s43
	s_addc_u32 s13, s13, 0
	s_waitcnt lgkmcnt(15)
	v_mfma_f32_16x16x32_bf16 v[168:171], v[68:71], v[44:47], 0
	v_mfma_f32_16x16x32_bf16 v[172:175], v[92:95], v[44:47], 0
	s_waitcnt lgkmcnt(12)
	v_mfma_f32_16x16x32_bf16 v[168:171], v[72:75], v[48:51], v[168:171]
	v_mfma_f32_16x16x32_bf16 v[172:175], v[96:99], v[48:51], v[172:175]
	s_waitcnt lgkmcnt(9)
	v_mfma_f32_16x16x32_bf16 v[168:171], v[76:79], v[52:55], v[168:171]
	v_mfma_f32_16x16x32_bf16 v[172:175], v[100:103], v[52:55], v[172:175]
	s_waitcnt lgkmcnt(6)
	v_mfma_f32_16x16x32_bf16 v[168:171], v[80:83], v[56:59], v[168:171]
	v_mfma_f32_16x16x32_bf16 v[172:175], v[104:107], v[56:59], v[172:175]
	s_waitcnt lgkmcnt(3)
	v_mfma_f32_16x16x32_bf16 v[168:171], v[84:87], v[60:63], v[168:171]
	v_mfma_f32_16x16x32_bf16 v[172:175], v[108:111], v[60:63], v[172:175]
	s_waitcnt lgkmcnt(0)
	v_mfma_f32_16x16x32_bf16 v[168:171], v[88:91], v[64:67], v[168:171]
	v_mfma_f32_16x16x32_bf16 v[172:175], v[112:115], v[64:67], v[172:175]
	ds_write_b16 v216, v32 offset:0
	ds_write_b16_d16_hi v215, v32 offset:0
	ds_write_b16 v214, v33 offset:0
	ds_write_b16_d16_hi v213, v33 offset:0
	ds_write_b16 v212, v34 offset:0
	ds_write_b16_d16_hi v211, v34 offset:0
	ds_write_b16 v210, v35 offset:0
	ds_write_b16_d16_hi v209, v35 offset:0
	global_load_dwordx4 v[20:23], v250, s[14:15]
	s_cmp_lt_u32 s33, 28
	s_cselect_b32 s43, 0x100000, 0
	s_add_u32 s14, s14, s43
	s_addc_u32 s15, s15, 0
	s_nop 7
	v_cvt_pk_bf16_f32 v184, v168, v169
	v_cvt_pk_bf16_f32 v185, v170, v171
	v_cvt_pk_bf16_f32 v186, v172, v173
	v_cvt_pk_bf16_f32 v187, v174, v175
	global_store_dwordx2 v248, v[184:185], s[18:19]
	global_store_dwordx2 v248, v[186:187], s[18:19] offset:32
	s_add_u32 s18, s18, 0x20000
	s_addc_u32 s19, s19, 0
	s_add_i32 s33, s33, 1
	s_waitcnt vmcnt(11)
	s_waitcnt lgkmcnt(0)
	s_barrier
	s_waitcnt vmcnt(0) lgkmcnt(0)
	s_barrier
	s_add_i32 s3, s3, s42
	s_cmpk_lt_i32 s3, 0x100
	s_cbranch_scc1 .Lp3O_item
	s_branch .Lp3_done

; #define LAS __attribute__((address_space(3)))
; __device__ __forceinline__ void gla_scan_item(const Ctx& C, int item, LAS unsigned char* lds, int tid) {
;     const int jx = item >> 3, bh = (item & 7) * 4 + (jx >> 3), sl = jx & 7, b = bh >> 2, h = bh & 3;
;     LAS bf16* Aq = (LAS bf16*)lds;
;     LAS bf16* Bc = (LAS bf16*)(lds + 25600);
;     LAS bf16* Kt = (LAS bf16*)(lds + 38400);
;     const int wave = tid >> 6, lane = tid & 63, l15 = lane & 15, quad = lane >> 4;
;     f32x4 S[2] = {(f32x4){0.f, 0.f, 0.f, 0.f}, (f32x4){0.f, 0.f, 0.f, 0.f}};
;     *(LAS u32x4*)(Bc + (tid >> 4) * 200 + (tid & 15) * 8) = (u32x4){0u, 0u, 0u, 0u};
;     u32x4 rq0A, rq1A, rsA, rk0A, rk1A, rvA = (u32x4){0u, 0u, 0u, 0u}; f32x4 rdA;
;     u32x4 rq0B, rq1B, rsB, rk0B, rk1B, rvB = (u32x4){0u, 0u, 0u, 0u}; f32x4 rdB;
.Lp3S_item:
	s_lshr_b32 s4, s3, 3
	s_and_b32 s41, s4, 7
	s_lshr_b32 s5, s4, 3
	s_and_b32 s37, s3, 7
	s_lshl_b32 s37, s37, 2
	s_add_i32 s37, s37, s5
	s_lshr_b32 s39, s37, 2
	s_and_b32 s40, s37, 3
	s_add_u32 s8, s94, 0x1d800000
	s_addc_u32 s9, s95, 0
	s_lshl_b32 s31, s39, 21
	s_add_u32 s8, s8, s31
	s_addc_u32 s9, s9, 0
	s_lshl_b32 s31, s40, 8
	s_add_u32 s8, s8, s31
	s_addc_u32 s9, s9, 0
	s_add_u32 s10, s94, 0x2f00000
	s_addc_u32 s11, s95, 0
	s_lshl_b32 s31, s37, 18
	s_add_u32 s10, s10, s31
	s_addc_u32 s11, s11, 0
	s_add_u32 s12, s94, 0x3700000
	s_addc_u32 s13, s95, 0
	s_lshl_b32 s31, s37, 19
	s_add_u32 s12, s12, s31
	s_addc_u32 s13, s13, 0
	s_add_u32 s16, s94, 0x2e00000
	s_addc_u32 s17, s95, 0
	s_lshl_b32 s31, s37, 14
	s_add_u32 s16, s16, s31
	s_addc_u32 s17, s17, 0
	s_add_u32 s34, s92, 0x4090000
	s_addc_u32 s35, s93, 0
	s_lshl_b32 s31, s37, 17
	s_add_u32 s34, s34, s31
	s_addc_u32 s35, s35, 0
	s_lshl_b32 s31, s41, 7
	s_add_u32 s34, s34, s31
	s_addc_u32 s35, s35, 0
	v_mov_b32_e32 v148, 0
	v_mov_b32_e32 v149, 0
	v_mov_b32_e32 v150, 0
	v_mov_b32_e32 v151, 0
	v_mov_b32_e32 v152, 0
	v_mov_b32_e32 v153, 0
	v_mov_b32_e32 v154, 0
	v_mov_b32_e32 v155, 0
	v_mov_b32_e32 v156, 0
	v_mov_b32_e32 v157, 0
	v_mov_b32_e32 v158, 0
	v_mov_b32_e32 v159, 0
	v_mov_b32_e32 v164, 0
	v_mov_b32_e32 v165, 0
	v_mov_b32_e32 v166, 0
	v_mov_b32_e32 v167, 0
	ds_write_b128 v245, v[188:191]
	s_mov_b32 m0, s46
	s_nop 0
	global_load_lds_dwordx4 v255, s[8:9]
	s_add_i32 m0, s46, 0x400
	s_nop 0
	global_load_lds_dwordx4 v254, s[8:9]
	s_mov_b32 m0, s47
	s_nop 0
	global_load_lds_dwordx4 v253, s[10:11]
	s_mov_b32 m0, s48
	s_nop 0
	global_load_lds_dwordx4 v252, s[12:13]
	s_add_i32 m0, s48, 0x400
	s_nop 0
	global_load_lds_dwordx4 v251, s[12:13]
	s_add_u32 s8, s8, 0x10000
	s_addc_u32 s9, s9, 0
	s_add_u32 s10, s10, 0x2000
	s_addc_u32 s11, s11, 0
	s_add_u32 s12, s12, 0x4000
	s_addc_u32 s13, s13, 0
	s_add_i32 m0, s46, 0xa000
	s_nop 0
	global_load_lds_dwordx4 v255, s[8:9]
	s_add_i32 m0, s46, 0xa400
	s_nop 0
	global_load_lds_dwordx4 v254, s[8:9]
	s_add_i32 m0, s47, 0xa000
	s_nop 0
	global_load_lds_dwordx4 v253, s[10:11]
	s_add_i32 m0, s48, 0xa000
	s_nop 0
	global_load_lds_dwordx4 v252, s[12:13]
	s_add_i32 m0, s48, 0xa400
	s_nop 0
	global_load_lds_dwordx4 v251, s[12:13]
	s_add_u32 s8, s8, 0x10000
	s_addc_u32 s9, s9, 0
	s_add_u32 s10, s10, 0x2000
	s_addc_u32 s11, s11, 0
	s_add_u32 s12, s12, 0x4000
	s_addc_u32 s13, s13, 0
	global_load_dwordx4 v[12:15], v249, s[16:17]
	global_load_dwordx4 v[16:19], v249, s[16:17] offset:64
	s_add_u32 s16, s16, 0x200
	s_addc_u32 s17, s17, 0
	global_load_dwordx4 v[24:27], v249, s[16:17]
	global_load_dwordx4 v[28:31], v249, s[16:17] offset:64
	s_add_u32 s16, s16, 0x200
	s_addc_u32 s17, s17, 0
	global_load_dwordx4 v[36:39], v249, s[16:17]
	global_load_dwordx4 v[40:43], v249, s[16:17] offset:64
	s_add_u32 s16, s16, 0x200
	s_addc_u32 s17, s17, 0
	s_waitcnt vmcnt(0)
	s_mov_b32 s33, 0
	s_waitcnt lgkmcnt(0)
	s_barrier
.Lp3S_loop:
	ds_read_b128 v[116:119], v230 offset:0
	ds_read_b128 v[132:135], v220 offset:0
	ds_read_b128 v[136:139], v220 offset:2048
	ds_read_b128 v[120:123], v230 offset:2048
	ds_read_b128 v[124:127], v229 offset:0
	ds_read_b128 v[140:143], v219 offset:0
	ds_read_b128 v[144:147], v219 offset:2048
	ds_read_b128 v[128:131], v229 offset:2048
	s_waitcnt vmcnt(14)
	v_pk_mul_f32 v[148:149], v[148:149], v[12:13]
	v_pk_mul_f32 v[150:151], v[150:151], v[14:15]
	v_pk_mul_f32 v[152:153], v[152:153], v[12:13]
	v_pk_mul_f32 v[154:155], v[154:155], v[14:15]
	v_pk_mul_f32 v[156:157], v[156:157], v[16:17]
	v_pk_mul_f32 v[158:159], v[158:159], v[18:19]
	v_pk_mul_f32 v[164:165], v[164:165], v[16:17]
	v_pk_mul_f32 v[166:167], v[166:167], v[18:19]
	s_add_i32 m0, s46, 0x14000
	s_nop 0
	global_load_lds_dwordx4 v255, s[8:9]
	s_add_i32 m0, s46, 0x14400
	s_nop 0
	global_load_lds_dwordx4 v254, s[8:9]
	s_add_i32 m0, s47, 0x14000
	s_nop 0
	global_load_lds_dwordx4 v253, s[10:11]
	s_add_i32 m0, s48, 0x14000
	s_nop 0
	global_load_lds_dwordx4 v252, s[12:13]
	s_add_i32 m0, s48, 0x14400
	s_nop 0
	global_load_lds_dwordx4 v251, s[12:13]
	s_cmp_lt_u32 s33, 29
	s_cselect_b32 s43, 0x10000, 0
	s_add_u32 s8, s8, s43
	s_addc_u32 s9, s9, 0
	s_cmp_lt_u32 s33, 29
	s_cselect_b32 s43, 0x2000, 0
	s_add_u32 s10, s10, s43
	s_addc_u32 s11, s11, 0
	s_cmp_lt_u32 s33, 29
	s_cselect_b32 s43, 0x4000, 0
	s_add_u32 s12, s12, s43
	s_addc_u32 s13, s13, 0
	s_waitcnt lgkmcnt(4)
	v_mfma_f32_16x16x32_bf16 v[148:151], v[116:119], v[132:135], v[148:151]
	v_mfma_f32_16x16x32_bf16 v[152:155], v[116:119], v[136:139], v[152:155]
	v_mfma_f32_16x16x32_bf16 v[156:159], v[120:123], v[132:135], v[156:159]
	v_mfma_f32_16x16x32_bf16 v[164:167], v[120:123], v[136:139], v[164:167]
	s_waitcnt lgkmcnt(0)
	v_mfma_f32_16x16x32_bf16 v[148:151], v[124:127], v[140:143], v[148:151]
	v_mfma_f32_16x16x32_bf16 v[152:155], v[124:127], v[144:147], v[152:155]
	v_mfma_f32_16x16x32_bf16 v[156:159], v[128:131], v[140:143], v[156:159]
	v_mfma_f32_16x16x32_bf16 v[164:167], v[128:131], v[144:147], v[164:167]
	global_load_dwordx4 v[12:15], v249, s[16:17]
	global_load_dwordx4 v[16:19], v249, s[16:17] offset:64
	s_cmp_lt_u32 s33, 28
	s_cselect_b32 s43, 0x200, 0
	s_add_u32 s16, s16, s43
	s_addc_u32 s17, s17, 0
	s_add_i32 s33, s33, 1
	s_nop 7
	s_nop 7
	v_cvt_pk_bf16_f32 v176, v148, v149
	v_cvt_pk_bf16_f32 v177, v150, v151
	ds_write_b64 v218, v[176:177] offset:12544
	v_cvt_pk_bf16_f32 v180, v152, v153
	v_cvt_pk_bf16_f32 v181, v154, v155
	ds_write_b64 v218, v[180:181] offset:16640
	s_nop 1
	v_cvt_pk_bf16_f32 v176, v156, v157
	v_cvt_pk_bf16_f32 v177, v158, v159
	ds_write_b64 v217, v[176:177] offset:12544
	v_cvt_pk_bf16_f32 v180, v164, v165
	v_cvt_pk_bf16_f32 v181, v166, v167
	ds_write_b64 v217, v[180:181] offset:16640
	s_waitcnt vmcnt(9)
	s_waitcnt lgkmcnt(0)
	s_barrier
	ds_read_b128 v[116:119], v230 offset:40960
	ds_read_b128 v[132:135], v220 offset:12288
	ds_read_b128 v[136:139], v220 offset:14336
	ds_read_b128 v[120:123], v230 offset:43008
	ds_read_b128 v[124:127], v229 offset:40960
	ds_read_b128 v[140:143], v219 offset:12288
	ds_read_b128 v[144:147], v219 offset:14336
	ds_read_b128 v[128:131], v229 offset:43008
	s_waitcnt vmcnt(14)
	v_pk_mul_f32 v[148:149], v[148:149], v[24:25]
	v_pk_mul_f32 v[150:151], v[150:151], v[26:27]
	v_pk_mul_f32 v[152:153], v[152:153], v[24:25]
	v_pk_mul_f32 v[154:155], v[154:155], v[26:27]
	v_pk_mul_f32 v[156:157], v[156:157], v[28:29]
	v_pk_mul_f32 v[158:159], v[158:159], v[30:31]
	v_pk_mul_f32 v[164:165], v[164:165], v[28:29]
	v_pk_mul_f32 v[166:167], v[166:167], v[30:31]
	s_mov_b32 m0, s46
	s_nop 0
	global_load_lds_dwordx4 v255, s[8:9]
	s_add_i32 m0, s46, 0x400
	s_nop 0
	global_load_lds_dwordx4 v254, s[8:9]
	s_mov_b32 m0, s47
	s_nop 0
	global_load_lds_dwordx4 v253, s[10:11]
	s_mov_b32 m0, s48
	s_nop 0
	global_load_lds_dwordx4 v252, s[12:13]
	s_add_i32 m0, s48, 0x400
	s_nop 0
	global_load_lds_dwordx4 v251, s[12:13]
	s_cmp_lt_u32 s33, 29
	s_cselect_b32 s43, 0x10000, 0
	s_add_u32 s8, s8, s43
	s_addc_u32 s9, s9, 0
	s_cmp_lt_u32 s33, 29
	s_cselect_b32 s43, 0x2000, 0
	s_add_u32 s10, s10, s43
	s_addc_u32 s11, s11, 0
	s_cmp_lt_u32 s33, 29
	s_cselect_b32 s43, 0x4000, 0
	s_add_u32 s12, s12, s43
	s_addc_u32 s13, s13, 0
	s_waitcnt lgkmcnt(4)
	v_mfma_f32_16x16x32_bf16 v[148:151], v[116:119], v[132:135], v[148:151]
	v_mfma_f32_16x16x32_bf16 v[152:155], v[116:119], v[136:139], v[152:155]
	v_mfma_f32_16x16x32_bf16 v[156:159], v[120:123], v[132:135], v[156:159]
	v_mfma_f32_16x16x32_bf16 v[164:167], v[120:123], v[136:139], v[164:167]
	s_waitcnt lgkmcnt(0)
	v_mfma_f32_16x16x32_bf16 v[148:151], v[124:127], v[140:143], v[148:151]
	v_mfma_f32_16x16x32_bf16 v[152:155], v[124:127], v[144:147], v[152:155]
	v_mfma_f32_16x16x32_bf16 v[156:159], v[128:131], v[140:143], v[156:159]
	v_mfma_f32_16x16x32_bf16 v[164:167], v[128:131], v[144:147], v[164:167]
	global_load_dwordx4 v[24:27], v249, s[16:17]
	global_load_dwordx4 v[28:31], v249, s[16:17] offset:64
	s_cmp_lt_u32 s33, 28
	s_cselect_b32 s43, 0x200, 0
	s_add_u32 s16, s16, s43
	s_addc_u32 s17, s17, 0
	s_add_i32 s33, s33, 1
	s_nop 7
	s_nop 7
	v_cvt_pk_bf16_f32 v176, v148, v149
	v_cvt_pk_bf16_f32 v177, v150, v151
	ds_write_b64 v218, v[176:177] offset:0
	v_cvt_pk_bf16_f32 v180, v152, v153
	v_cvt_pk_bf16_f32 v181, v154, v155
	ds_write_b64 v218, v[180:181] offset:4096
	s_nop 1
	v_cvt_pk_bf16_f32 v176, v156, v157
	v_cvt_pk_bf16_f32 v177, v158, v159
	ds_write_b64 v217, v[176:177] offset:0
	v_cvt_pk_bf16_f32 v180, v164, v165
	v_cvt_pk_bf16_f32 v181, v166, v167
	ds_write_b64 v217, v[180:181] offset:4096
	s_waitcnt vmcnt(9)
	s_waitcnt lgkmcnt(0)
	s_barrier
	ds_read_b128 v[116:119], v228 offset:0
	ds_read_b128 v[132:135], v220 offset:0
	ds_read_b128 v[136:139], v220 offset:2048
	ds_read_b128 v[120:123], v228 offset:2048
	ds_read_b128 v[124:127], v227 offset:0
	ds_read_b128 v[140:143], v219 offset:0
	ds_read_b128 v[144:147], v219 offset:2048
	ds_read_b128 v[128:131], v227 offset:2048
	s_waitcnt vmcnt(14)
	v_pk_mul_f32 v[148:149], v[148:149], v[36:37]
	v_pk_mul_f32 v[150:151], v[150:151], v[38:39]
	v_pk_mul_f32 v[152:153], v[152:153], v[36:37]
	v_pk_mul_f32 v[154:155], v[154:155], v[38:39]
	v_pk_mul_f32 v[156:157], v[156:157], v[40:41]
	v_pk_mul_f32 v[158:159], v[158:159], v[42:43]
	v_pk_mul_f32 v[164:165], v[164:165], v[40:41]
	v_pk_mul_f32 v[166:167], v[166:167], v[42:43]
	s_add_i32 m0, s46, 0xa000
	s_nop 0
	global_load_lds_dwordx4 v255, s[8:9]
	s_add_i32 m0, s46, 0xa400
	s_nop 0
	global_load_lds_dwordx4 v254, s[8:9]
	s_add_i32 m0, s47, 0xa000
	s_nop 0
	global_load_lds_dwordx4 v253, s[10:11]
	s_add_i32 m0, s48, 0xa000
	s_nop 0
	global_load_lds_dwordx4 v252, s[12:13]
	s_add_i32 m0, s48, 0xa400
	s_nop 0
	global_load_lds_dwordx4 v251, s[12:13]
	s_cmp_lt_u32 s33, 29
	s_cselect_b32 s43, 0x10000, 0
	s_add_u32 s8, s8, s43
	s_addc_u32 s9, s9, 0
	s_cmp_lt_u32 s33, 29
	s_cselect_b32 s43, 0x2000, 0
	s_add_u32 s10, s10, s43
	s_addc_u32 s11, s11, 0
	s_cmp_lt_u32 s33, 29
	s_cselect_b32 s43, 0x4000, 0
	s_add_u32 s12, s12, s43
	s_addc_u32 s13, s13, 0
	s_waitcnt lgkmcnt(4)
	v_mfma_f32_16x16x32_bf16 v[148:151], v[116:119], v[132:135], v[148:151]
	v_mfma_f32_16x16x32_bf16 v[152:155], v[116:119], v[136:139], v[152:155]
	v_mfma_f32_16x16x32_bf16 v[156:159], v[120:123], v[132:135], v[156:159]
	v_mfma_f32_16x16x32_bf16 v[164:167], v[120:123], v[136:139], v[164:167]
	s_waitcnt lgkmcnt(0)
	v_mfma_f32_16x16x32_bf16 v[148:151], v[124:127], v[140:143], v[148:151]
	v_mfma_f32_16x16x32_bf16 v[152:155], v[124:127], v[144:147], v[152:155]
	v_mfma_f32_16x16x32_bf16 v[156:159], v[128:131], v[140:143], v[156:159]
	v_mfma_f32_16x16x32_bf16 v[164:167], v[128:131], v[144:147], v[164:167]
	global_load_dwordx4 v[36:39], v249, s[16:17]
	global_load_dwordx4 v[40:43], v249, s[16:17] offset:64
	s_cmp_lt_u32 s33, 28
	s_cselect_b32 s43, 0x200, 0
	s_add_u32 s16, s16, s43
	s_addc_u32 s17, s17, 0
	s_add_i32 s33, s33, 1
	s_nop 7
	s_nop 7
	v_cvt_pk_bf16_f32 v176, v148, v149
	v_cvt_pk_bf16_f32 v177, v150, v151
	ds_write_b64 v218, v[176:177] offset:12544
	v_cvt_pk_bf16_f32 v180, v152, v153
	v_cvt_pk_bf16_f32 v181, v154, v155
	ds_write_b64 v218, v[180:181] offset:16640
	s_nop 1
	v_cvt_pk_bf16_f32 v176, v156, v157
	v_cvt_pk_bf16_f32 v177, v158, v159
	ds_write_b64 v217, v[176:177] offset:12544
	v_cvt_pk_bf16_f32 v180, v164, v165
	v_cvt_pk_bf16_f32 v181, v166, v167
	ds_write_b64 v217, v[180:181] offset:16640
	s_waitcnt vmcnt(9)
	s_waitcnt lgkmcnt(0)
	s_barrier
	ds_read_b128 v[116:119], v230 offset:0
	ds_read_b128 v[132:135], v220 offset:12288
	ds_read_b128 v[136:139], v220 offset:14336
	ds_read_b128 v[120:123], v230 offset:2048
	ds_read_b128 v[124:127], v229 offset:0
	ds_read_b128 v[140:143], v219 offset:12288
	ds_read_b128 v[144:147], v219 offset:14336
	ds_read_b128 v[128:131], v229 offset:2048
	s_waitcnt vmcnt(14)
	v_pk_mul_f32 v[148:149], v[148:149], v[12:13]
	v_pk_mul_f32 v[150:151], v[150:151], v[14:15]
	v_pk_mul_f32 v[152:153], v[152:153], v[12:13]
	v_pk_mul_f32 v[154:155], v[154:155], v[14:15]
	v_pk_mul_f32 v[156:157], v[156:157], v[16:17]
	v_pk_mul_f32 v[158:159], v[158:159], v[18:19]
	v_pk_mul_f32 v[164:165], v[164:165], v[16:17]
	v_pk_mul_f32 v[166:167], v[166:167], v[18:19]
	s_add_i32 m0, s46, 0x14000
	s_nop 0
	global_load_lds_dwordx4 v255, s[8:9]
	s_add_i32 m0, s46, 0x14400
	s_nop 0
	global_load_lds_dwordx4 v254, s[8:9]
	s_add_i32 m0, s47, 0x14000
	s_nop 0
	global_load_lds_dwordx4 v253, s[10:11]
	s_add_i32 m0, s48, 0x14000
	s_nop 0
	global_load_lds_dwordx4 v252, s[12:13]
	s_add_i32 m0, s48, 0x14400
	s_nop 0
	global_load_lds_dwordx4 v251, s[12:13]
	s_cmp_lt_u32 s33, 29
	s_cselect_b32 s43, 0x10000, 0
	s_add_u32 s8, s8, s43
	s_addc_u32 s9, s9, 0
	s_cmp_lt_u32 s33, 29
	s_cselect_b32 s43, 0x2000, 0
	s_add_u32 s10, s10, s43
	s_addc_u32 s11, s11, 0
	s_cmp_lt_u32 s33, 29
	s_cselect_b32 s43, 0x4000, 0
	s_add_u32 s12, s12, s43
	s_addc_u32 s13, s13, 0
	s_waitcnt lgkmcnt(4)
	v_mfma_f32_16x16x32_bf16 v[148:151], v[116:119], v[132:135], v[148:151]
	v_mfma_f32_16x16x32_bf16 v[152:155], v[116:119], v[136:139], v[152:155]
	v_mfma_f32_16x16x32_bf16 v[156:159], v[120:123], v[132:135], v[156:159]
	v_mfma_f32_16x16x32_bf16 v[164:167], v[120:123], v[136:139], v[164:167]
	s_waitcnt lgkmcnt(0)
	v_mfma_f32_16x16x32_bf16 v[148:151], v[124:127], v[140:143], v[148:151]
	v_mfma_f32_16x16x32_bf16 v[152:155], v[124:127], v[144:147], v[152:155]
	v_mfma_f32_16x16x32_bf16 v[156:159], v[128:131], v[140:143], v[156:159]
	v_mfma_f32_16x16x32_bf16 v[164:167], v[128:131], v[144:147], v[164:167]
	global_load_dwordx4 v[12:15], v249, s[16:17]
	global_load_dwordx4 v[16:19], v249, s[16:17] offset:64
	s_cmp_lt_u32 s33, 28
	s_cselect_b32 s43, 0x200, 0
	s_add_u32 s16, s16, s43
	s_addc_u32 s17, s17, 0
	s_add_i32 s33, s33, 1
	s_nop 7
	s_nop 7
	v_cvt_pk_bf16_f32 v176, v148, v149
	v_cvt_pk_bf16_f32 v177, v150, v151
	ds_write_b64 v218, v[176:177] offset:0
	v_cvt_pk_bf16_f32 v180, v152, v153
	v_cvt_pk_bf16_f32 v181, v154, v155
	ds_write_b64 v218, v[180:181] offset:4096
	s_nop 1
	v_cvt_pk_bf16_f32 v176, v156, v157
	v_cvt_pk_bf16_f32 v177, v158, v159
	ds_write_b64 v217, v[176:177] offset:0
	v_cvt_pk_bf16_f32 v180, v164, v165
	v_cvt_pk_bf16_f32 v181, v166, v167
	ds_write_b64 v217, v[180:181] offset:4096
	s_waitcnt vmcnt(9)
	s_waitcnt lgkmcnt(0)
	s_barrier
	ds_read_b128 v[116:119], v230 offset:40960
	ds_read_b128 v[132:135], v220 offset:0
	ds_read_b128 v[136:139], v220 offset:2048
	ds_read_b128 v[120:123], v230 offset:43008
	ds_read_b128 v[124:127], v229 offset:40960
	ds_read_b128 v[140:143], v219 offset:0
	ds_read_b128 v[144:147], v219 offset:2048
	ds_read_b128 v[128:131], v229 offset:43008
	s_waitcnt vmcnt(14)
	v_pk_mul_f32 v[148:149], v[148:149], v[24:25]
	v_pk_mul_f32 v[150:151], v[150:151], v[26:27]
	v_pk_mul_f32 v[152:153], v[152:153], v[24:25]
	v_pk_mul_f32 v[154:155], v[154:155], v[26:27]
	v_pk_mul_f32 v[156:157], v[156:157], v[28:29]
	v_pk_mul_f32 v[158:159], v[158:159], v[30:31]
	v_pk_mul_f32 v[164:165], v[164:165], v[28:29]
	v_pk_mul_f32 v[166:167], v[166:167], v[30:31]
	s_mov_b32 m0, s46
	s_nop 0
	global_load_lds_dwordx4 v255, s[8:9]
	s_add_i32 m0, s46, 0x400
	s_nop 0
	global_load_lds_dwordx4 v254, s[8:9]
	s_mov_b32 m0, s47
	s_nop 0
	global_load_lds_dwordx4 v253, s[10:11]
	s_mov_b32 m0, s48
	s_nop 0
	global_load_lds_dwordx4 v252, s[12:13]
	s_add_i32 m0, s48, 0x400
	s_nop 0
	global_load_lds_dwordx4 v251, s[12:13]
	s_cmp_lt_u32 s33, 29
	s_cselect_b32 s43, 0x10000, 0
	s_add_u32 s8, s8, s43
	s_addc_u32 s9, s9, 0
	s_cmp_lt_u32 s33, 29
	s_cselect_b32 s43, 0x2000, 0
	s_add_u32 s10, s10, s43
	s_addc_u32 s11, s11, 0
	s_cmp_lt_u32 s33, 29
	s_cselect_b32 s43, 0x4000, 0
	s_add_u32 s12, s12, s43
	s_addc_u32 s13, s13, 0
	s_waitcnt lgkmcnt(4)
	v_mfma_f32_16x16x32_bf16 v[148:151], v[116:119], v[132:135], v[148:151]
	v_mfma_f32_16x16x32_bf16 v[152:155], v[116:119], v[136:139], v[152:155]
	v_mfma_f32_16x16x32_bf16 v[156:159], v[120:123], v[132:135], v[156:159]
	v_mfma_f32_16x16x32_bf16 v[164:167], v[120:123], v[136:139], v[164:167]
	s_waitcnt lgkmcnt(0)
	v_mfma_f32_16x16x32_bf16 v[148:151], v[124:127], v[140:143], v[148:151]
	v_mfma_f32_16x16x32_bf16 v[152:155], v[124:127], v[144:147], v[152:155]
	v_mfma_f32_16x16x32_bf16 v[156:159], v[128:131], v[140:143], v[156:159]
	v_mfma_f32_16x16x32_bf16 v[164:167], v[128:131], v[144:147], v[164:167]
	global_load_dwordx4 v[24:27], v249, s[16:17]
	global_load_dwordx4 v[28:31], v249, s[16:17] offset:64
	s_cmp_lt_u32 s33, 28
	s_cselect_b32 s43, 0x200, 0
	s_add_u32 s16, s16, s43
	s_addc_u32 s17, s17, 0
	s_add_i32 s33, s33, 1
	s_nop 7
	s_nop 7
	v_cvt_pk_bf16_f32 v176, v148, v149
	v_cvt_pk_bf16_f32 v177, v150, v151
	ds_write_b64 v218, v[176:177] offset:12544
	v_cvt_pk_bf16_f32 v180, v152, v153
	v_cvt_pk_bf16_f32 v181, v154, v155
	ds_write_b64 v218, v[180:181] offset:16640
	s_nop 1
	v_cvt_pk_bf16_f32 v176, v156, v157
	v_cvt_pk_bf16_f32 v177, v158, v159
	ds_write_b64 v217, v[176:177] offset:12544
	v_cvt_pk_bf16_f32 v180, v164, v165
	v_cvt_pk_bf16_f32 v181, v166, v167
	ds_write_b64 v217, v[180:181] offset:16640
	s_waitcnt vmcnt(9)
	s_waitcnt lgkmcnt(0)
	s_barrier
; __device__ __forceinline__ void gla_scan_item(const Ctx& C, int item, LAS unsigned char* lds, int tid) {
;     ...
;     SCAN_LOAD(A, 0); SCAN_LOAD(B, 1);
; #pragma unroll
;     for (int n = 0; n < 32; n += 2) { SCAN_STEP(A, n); SCAN_STEP(B, n + 1); }
	ds_read_b128 v[116:119], v228 offset:0
	ds_read_b128 v[132:135], v220 offset:12288
	ds_read_b128 v[136:139], v220 offset:14336
	ds_read_b128 v[120:123], v228 offset:2048
	ds_read_b128 v[124:127], v227 offset:0
	ds_read_b128 v[140:143], v219 offset:12288
	ds_read_b128 v[144:147], v219 offset:14336
	ds_read_b128 v[128:131], v227 offset:2048
	s_waitcnt vmcnt(14)
	v_pk_mul_f32 v[148:149], v[148:149], v[36:37]
	v_pk_mul_f32 v[150:151], v[150:151], v[38:39]
	v_pk_mul_f32 v[152:153], v[152:153], v[36:37]
	v_pk_mul_f32 v[154:155], v[154:155], v[38:39]
	v_pk_mul_f32 v[156:157], v[156:157], v[40:41]
	v_pk_mul_f32 v[158:159], v[158:159], v[42:43]
	v_pk_mul_f32 v[164:165], v[164:165], v[40:41]
	v_pk_mul_f32 v[166:167], v[166:167], v[42:43]
	s_add_i32 m0, s46, 0xa000
	s_nop 0
	global_load_lds_dwordx4 v255, s[8:9]
	s_add_i32 m0, s46, 0xa400
	s_nop 0
	global_load_lds_dwordx4 v254, s[8:9]
	s_add_i32 m0, s47, 0xa000
	s_nop 0
	global_load_lds_dwordx4 v253, s[10:11]
	s_add_i32 m0, s48, 0xa000
	s_nop 0
	global_load_lds_dwordx4 v252, s[12:13]
	s_add_i32 m0, s48, 0xa400
	s_nop 0
	global_load_lds_dwordx4 v251, s[12:13]
	s_cmp_lt_u32 s33, 29
	s_cselect_b32 s43, 0x10000, 0
	s_add_u32 s8, s8, s43
	s_addc_u32 s9, s9, 0
	s_cmp_lt_u32 s33, 29
	s_cselect_b32 s43, 0x2000, 0
	s_add_u32 s10, s10, s43
	s_addc_u32 s11, s11, 0
	s_cmp_lt_u32 s33, 29
	s_cselect_b32 s43, 0x4000, 0
	s_add_u32 s12, s12, s43
	s_addc_u32 s13, s13, 0
	s_waitcnt lgkmcnt(4)
	v_mfma_f32_16x16x32_bf16 v[148:151], v[116:119], v[132:135], v[148:151]
	v_mfma_f32_16x16x32_bf16 v[152:155], v[116:119], v[136:139], v[152:155]
	v_mfma_f32_16x16x32_bf16 v[156:159], v[120:123], v[132:135], v[156:159]
	v_mfma_f32_16x16x32_bf16 v[164:167], v[120:123], v[136:139], v[164:167]
	s_waitcnt lgkmcnt(0)
	v_mfma_f32_16x16x32_bf16 v[148:151], v[124:127], v[140:143], v[148:151]
	v_mfma_f32_16x16x32_bf16 v[152:155], v[124:127], v[144:147], v[152:155]
	v_mfma_f32_16x16x32_bf16 v[156:159], v[128:131], v[140:143], v[156:159]
	v_mfma_f32_16x16x32_bf16 v[164:167], v[128:131], v[144:147], v[164:167]
	global_load_dwordx4 v[36:39], v249, s[16:17]
	global_load_dwordx4 v[40:43], v249, s[16:17] offset:64
	s_cmp_lt_u32 s33, 28
	s_cselect_b32 s43, 0x200, 0
	s_add_u32 s16, s16, s43
	s_addc_u32 s17, s17, 0
	s_add_i32 s33, s33, 1
	s_nop 7
	s_nop 7
	v_cvt_pk_bf16_f32 v176, v148, v149
	v_cvt_pk_bf16_f32 v177, v150, v151
	ds_write_b64 v218, v[176:177] offset:0
	v_cvt_pk_bf16_f32 v180, v152, v153
	v_cvt_pk_bf16_f32 v181, v154, v155
	ds_write_b64 v218, v[180:181] offset:4096
	s_nop 1
	v_cvt_pk_bf16_f32 v176, v156, v157
	v_cvt_pk_bf16_f32 v177, v158, v159
	ds_write_b64 v217, v[176:177] offset:0
	v_cvt_pk_bf16_f32 v180, v164, v165
	v_cvt_pk_bf16_f32 v181, v166, v167
	ds_write_b64 v217, v[180:181] offset:4096
	s_waitcnt vmcnt(9)
	s_waitcnt lgkmcnt(0)
	s_barrier
	s_cmp_lt_u32 s33, 30
	s_cbranch_scc1 .Lp3S_loop
	ds_read_b128 v[116:119], v230 offset:0
	ds_read_b128 v[132:135], v220 offset:0
	ds_read_b128 v[136:139], v220 offset:2048
	ds_read_b128 v[120:123], v230 offset:2048
	ds_read_b128 v[124:127], v229 offset:0
	ds_read_b128 v[140:143], v219 offset:0
	ds_read_b128 v[144:147], v219 offset:2048
	ds_read_b128 v[128:131], v229 offset:2048
	s_waitcnt vmcnt(14)
	v_pk_mul_f32 v[148:149], v[148:149], v[12:13]
	v_pk_mul_f32 v[150:151], v[150:151], v[14:15]
	v_pk_mul_f32 v[152:153], v[152:153], v[12:13]
	v_pk_mul_f32 v[154:155], v[154:155], v[14:15]
	v_pk_mul_f32 v[156:157], v[156:157], v[16:17]
	v_pk_mul_f32 v[158:159], v[158:159], v[18:19]
	v_pk_mul_f32 v[164:165], v[164:165], v[16:17]
	v_pk_mul_f32 v[166:167], v[166:167], v[18:19]
	s_add_i32 m0, s46, 0x14000
	s_nop 0
	global_load_lds_dwordx4 v255, s[8:9]
	s_add_i32 m0, s46, 0x14400
	s_nop 0
	global_load_lds_dwordx4 v254, s[8:9]
	s_add_i32 m0, s47, 0x14000
	s_nop 0
	global_load_lds_dwordx4 v253, s[10:11]
	s_add_i32 m0, s48, 0x14000
	s_nop 0
	global_load_lds_dwordx4 v252, s[12:13]
	s_add_i32 m0, s48, 0x14400
	s_nop 0
	global_load_lds_dwordx4 v251, s[12:13]
	s_cmp_lt_u32 s33, 29
	s_cselect_b32 s43, 0x10000, 0
	s_add_u32 s8, s8, s43
	s_addc_u32 s9, s9, 0
	s_cmp_lt_u32 s33, 29
	s_cselect_b32 s43, 0x2000, 0
	s_add_u32 s10, s10, s43
	s_addc_u32 s11, s11, 0
	s_cmp_lt_u32 s33, 29
	s_cselect_b32 s43, 0x4000, 0
	s_add_u32 s12, s12, s43
	s_addc_u32 s13, s13, 0
	s_waitcnt lgkmcnt(4)
	v_mfma_f32_16x16x32_bf16 v[148:151], v[116:119], v[132:135], v[148:151]
	v_mfma_f32_16x16x32_bf16 v[152:155], v[116:119], v[136:139], v[152:155]
	v_mfma_f32_16x16x32_bf16 v[156:159], v[120:123], v[132:135], v[156:159]
	v_mfma_f32_16x16x32_bf16 v[164:167], v[120:123], v[136:139], v[164:167]
	s_waitcnt lgkmcnt(0)
	v_mfma_f32_16x16x32_bf16 v[148:151], v[124:127], v[140:143], v[148:151]
	v_mfma_f32_16x16x32_bf16 v[152:155], v[124:127], v[144:147], v[152:155]
	v_mfma_f32_16x16x32_bf16 v[156:159], v[128:131], v[140:143], v[156:159]
	v_mfma_f32_16x16x32_bf16 v[164:167], v[128:131], v[144:147], v[164:167]
	global_load_dwordx4 v[12:15], v249, s[16:17]
	global_load_dwordx4 v[16:19], v249, s[16:17] offset:64
	s_cmp_lt_u32 s33, 28
	s_cselect_b32 s43, 0x200, 0
	s_add_u32 s16, s16, s43
	s_addc_u32 s17, s17, 0
	s_add_i32 s33, s33, 1
	s_nop 7
	s_nop 7
	v_cvt_pk_bf16_f32 v176, v148, v149
	v_cvt_pk_bf16_f32 v177, v150, v151
	ds_write_b64 v218, v[176:177] offset:12544
	v_cvt_pk_bf16_f32 v180, v152, v153
	v_cvt_pk_bf16_f32 v181, v154, v155
	ds_write_b64 v218, v[180:181] offset:16640
	s_nop 1
	v_cvt_pk_bf16_f32 v176, v156, v157
	v_cvt_pk_bf16_f32 v177, v158, v159
	ds_write_b64 v217, v[176:177] offset:12544
	v_cvt_pk_bf16_f32 v180, v164, v165
	v_cvt_pk_bf16_f32 v181, v166, v167
	ds_write_b64 v217, v[180:181] offset:16640
	s_waitcnt vmcnt(9)
	s_waitcnt lgkmcnt(0)
	s_barrier
; __device__ __forceinline__ void gla_scan_item(const Ctx& C, int item, LAS unsigned char* lds, int tid) {
;     ...
;     SCAN_LOAD(A, 0); SCAN_LOAD(B, 1);
; #pragma unroll
;     for (int n = 0; n < 32; n += 2) { SCAN_STEP(A, n); SCAN_STEP(B, n + 1); }
;     ...
;     float* So = C.out + OUT_GLAP + ((size_t)bh * 128 + wave * 16 + quad * 4) * 256 + sl * 32 + l15;
; #pragma unroll
;     for (int v2 = 0; v2 < 2; ++v2)
; #pragma unroll
;         for (int j = 0; j < 4; ++j) So[(size_t)j * 256 + v2 * 16] = S[v2][j];
;     __syncthreads();
	ds_read_b128 v[116:119], v230 offset:40960
	ds_read_b128 v[132:135], v220 offset:12288
	ds_read_b128 v[136:139], v220 offset:14336
	ds_read_b128 v[120:123], v230 offset:43008
	ds_read_b128 v[124:127], v229 offset:40960
	ds_read_b128 v[140:143], v219 offset:12288
	ds_read_b128 v[144:147], v219 offset:14336
	ds_read_b128 v[128:131], v229 offset:43008
	s_waitcnt vmcnt(14)
	v_pk_mul_f32 v[148:149], v[148:149], v[24:25]
	v_pk_mul_f32 v[150:151], v[150:151], v[26:27]
	v_pk_mul_f32 v[152:153], v[152:153], v[24:25]
	v_pk_mul_f32 v[154:155], v[154:155], v[26:27]
	v_pk_mul_f32 v[156:157], v[156:157], v[28:29]
	v_pk_mul_f32 v[158:159], v[158:159], v[30:31]
	v_pk_mul_f32 v[164:165], v[164:165], v[28:29]
	v_pk_mul_f32 v[166:167], v[166:167], v[30:31]
	s_mov_b32 m0, s46
	s_nop 0
	global_load_lds_dwordx4 v255, s[8:9]
	s_add_i32 m0, s46, 0x400
	s_nop 0
	global_load_lds_dwordx4 v254, s[8:9]
	s_mov_b32 m0, s47
	s_nop 0
	global_load_lds_dwordx4 v253, s[10:11]
	s_mov_b32 m0, s48
	s_nop 0
	global_load_lds_dwordx4 v252, s[12:13]
	s_add_i32 m0, s48, 0x400
	s_nop 0
	global_load_lds_dwordx4 v251, s[12:13]
	s_cmp_lt_u32 s33, 29
	s_cselect_b32 s43, 0x10000, 0
	s_add_u32 s8, s8, s43
	s_addc_u32 s9, s9, 0
	s_cmp_lt_u32 s33, 29
	s_cselect_b32 s43, 0x2000, 0
	s_add_u32 s10, s10, s43
	s_addc_u32 s11, s11, 0
	s_cmp_lt_u32 s33, 29
	s_cselect_b32 s43, 0x4000, 0
	s_add_u32 s12, s12, s43
	s_addc_u32 s13, s13, 0
	s_waitcnt lgkmcnt(4)
	v_mfma_f32_16x16x32_bf16 v[148:151], v[116:119], v[132:135], v[148:151]
	v_mfma_f32_16x16x32_bf16 v[152:155], v[116:119], v[136:139], v[152:155]
	v_mfma_f32_16x16x32_bf16 v[156:159], v[120:123], v[132:135], v[156:159]
	v_mfma_f32_16x16x32_bf16 v[164:167], v[120:123], v[136:139], v[164:167]
	s_waitcnt lgkmcnt(0)
	v_mfma_f32_16x16x32_bf16 v[148:151], v[124:127], v[140:143], v[148:151]
	v_mfma_f32_16x16x32_bf16 v[152:155], v[124:127], v[144:147], v[152:155]
	v_mfma_f32_16x16x32_bf16 v[156:159], v[128:131], v[140:143], v[156:159]
	v_mfma_f32_16x16x32_bf16 v[164:167], v[128:131], v[144:147], v[164:167]
	global_load_dwordx4 v[24:27], v249, s[16:17]
	global_load_dwordx4 v[28:31], v249, s[16:17] offset:64
	s_cmp_lt_u32 s33, 28
	s_cselect_b32 s43, 0x200, 0
	s_add_u32 s16, s16, s43
	s_addc_u32 s17, s17, 0
	s_add_i32 s33, s33, 1
	s_nop 7
	s_nop 7
	v_cvt_pk_bf16_f32 v176, v148, v149
	v_cvt_pk_bf16_f32 v177, v150, v151
	ds_write_b64 v218, v[176:177] offset:0
	v_cvt_pk_bf16_f32 v180, v152, v153
	v_cvt_pk_bf16_f32 v181, v154, v155
	ds_write_b64 v218, v[180:181] offset:4096
	s_nop 1
	v_cvt_pk_bf16_f32 v176, v156, v157
	v_cvt_pk_bf16_f32 v177, v158, v159
	ds_write_b64 v217, v[176:177] offset:0
	v_cvt_pk_bf16_f32 v180, v164, v165
	v_cvt_pk_bf16_f32 v181, v166, v167
	ds_write_b64 v217, v[180:181] offset:4096
	s_waitcnt vmcnt(9)
	s_waitcnt lgkmcnt(0)
	s_barrier
	s_nop 7
	global_store_dword v247, v148, s[34:35] offset:0
	global_store_dword v247, v149, s[34:35] offset:1024
	global_store_dword v247, v150, s[34:35] offset:2048
	global_store_dword v247, v151, s[34:35] offset:3072
	global_store_dword v247, v152, s[34:35] offset:64
	global_store_dword v247, v153, s[34:35] offset:1088
	global_store_dword v247, v154, s[34:35] offset:2112
	global_store_dword v247, v155, s[34:35] offset:3136
	global_store_dword v246, v156, s[34:35] offset:0
	global_store_dword v246, v157, s[34:35] offset:1024
	global_store_dword v246, v158, s[34:35] offset:2048
	global_store_dword v246, v159, s[34:35] offset:3072
	global_store_dword v246, v164, s[34:35] offset:64
	global_store_dword v246, v165, s[34:35] offset:1088
	global_store_dword v246, v166, s[34:35] offset:2112
	global_store_dword v246, v167, s[34:35] offset:3136
	s_waitcnt vmcnt(0) lgkmcnt(0)
	s_barrier
	s_add_i32 s3, s3, s42
	s_cmpk_lt_i32 s3, 0x100
	s_cbranch_scc1 .Lp3S_item
	s_branch .Lp3_done
.Lp3_done:
.LBB0_496:
	s_cmp_gt_i32 s97, 4
	s_cselect_b64 s[4:5], -1, 0
	s_and_b64 s[0:1], s[0:1], s[4:5]
	v_readlane_b32 s70, v237, 45
	v_readlane_b32 s74, v237, 43
	s_andn2_b64 vcc, exec, s[0:1]
	v_readlane_b32 s71, v237, 46
	v_readlane_b32 s75, v237, 44
	s_cbranch_vccnz .LBB0_550
	s_waitcnt vmcnt(0)
	s_waitcnt vmcnt(0)
	s_barrier
	s_mov_b64 s[0:1], exec
	v_readlane_b32 s8, v237, 3
	v_readlane_b32 s9, v237, 4
	s_and_b64 s[8:9], s[0:1], s[8:9]
	s_mov_b64 exec, s[8:9]
	s_cbranch_execz .LBB0_549
	s_add_i32 s3, 0, 0x20000
	v_mov_b32_e32 v0, s3
	s_waitcnt vmcnt(0) expcnt(0) lgkmcnt(0)
	ds_read_b32 v2, v0
	s_add_i32 s3, 0, 0x20004
	v_mov_b32_e32 v0, s3
	ds_read_b32 v0, v0
	s_waitcnt lgkmcnt(1)
	v_cmp_ne_u32_e32 vcc, 0, v2
	s_cbranch_vccnz .LBB0_513
	v_readlane_b32 s8, v237, 0
	v_readlane_b32 s9, v237, 1
	s_load_dwordx2 s[10:11], s[8:9], 0x4
	s_add_u32 s8, s94, 0x2d40200
	s_addc_u32 s9, s95, 0
	s_add_u32 s12, s94, 0x2d40400
	s_addc_u32 s13, s95, 0
	s_add_u32 s14, s94, 0x2d40500
	s_addc_u32 s15, s95, 0
	s_add_u32 s16, s94, 0x2d40600
	s_addc_u32 s17, s95, 0
	s_add_u32 s18, s94, 0x2d40700
	s_addc_u32 s19, s95, 0
	s_add_u32 s20, s94, 0x2d40800
	s_addc_u32 s21, s95, 0
	s_add_u32 s22, s94, 0x2d40900
	s_addc_u32 s23, s95, 0
	s_add_u32 s24, s94, 0x2d40a00
	s_addc_u32 s25, s95, 0
	s_add_u32 s26, s94, 0x2d40b00
	s_addc_u32 s27, s95, 0
	s_add_u32 s28, s94, 0x2d40c00
	s_addc_u32 s29, s95, 0
	s_add_u32 s30, s94, 0x2d40d00
	s_addc_u32 s31, s95, 0
	s_add_u32 s34, s94, 0x2d40e00
	s_addc_u32 s35, s95, 0
	s_add_u32 s36, s94, 0x2d40f00
	s_addc_u32 s37, s95, 0
	s_add_u32 s38, s94, 0x2d41000
	s_addc_u32 s39, s95, 0
	s_add_u32 s50, s94, 0x2d41100
	s_addc_u32 s51, s95, 0
	s_add_u32 s52, s94, 0x2d41200
	s_addc_u32 s53, s95, 0
	s_waitcnt lgkmcnt(0)
	s_mul_i32 s3, s10, s42
	s_add_u32 s58, s94, 0x2d41300
	s_mul_i32 s3, s3, s11
	s_addc_u32 s59, s95, 0
	s_mov_b32 s10, 1
	v_mov_b32_e32 v16, 0
	s_branch .LBB0_501
